# ph027
# speedup vs baseline: 1.0328x; 1.0328x over previous
.LBB0_31:
	s_or_b64 exec, exec, s[6:7]
	v_mov_b32_e32 v1, v208
	s_lshl_b32 s6, s23, 8
	v_lshrrev_b32_e32 v130, 1, v1
	v_and_b32_e32 v130, 0x78, v130
	v_or_b32_e32 v134, s30, v130
	v_ashrrev_i32_e32 v130, 2, v1
	v_and_b32_e32 v130, 0xffffffc0, v130
	v_and_or_b32 v1, v1, 15, s6
	s_load_dwordx2 s[6:7], s[0:1], 0xc0
	v_add_u32_e32 v132, v1, v130
	v_lshlrev_b32_e32 v138, 2, v134
	v_or_b32_e32 v134, 16, v132
	v_ashrrev_i32_e32 v135, 31, v134
	v_lshlrev_b64 v[134:135], 12, v[134:135]
	v_ashrrev_i32_e32 v133, 31, v132
	v_mov_b32_e32 v139, v0
	s_waitcnt lgkmcnt(0)
	v_lshl_add_u64 v[134:135], s[6:7], 0, v[134:135]
	v_lshlrev_b64 v[130:131], 12, v[132:133]
	v_lshl_add_u64 v[136:137], v[134:135], 0, v[138:139]
	v_or_b32_e32 v134, 32, v132
	v_or_b32_e32 v132, 48, v132
	v_ashrrev_i32_e32 v135, 31, v134
	v_ashrrev_i32_e32 v133, 31, v132
	v_lshl_add_u64 v[130:131], s[6:7], 0, v[130:131]
	v_lshlrev_b64 v[134:135], 12, v[134:135]
	v_lshlrev_b64 v[132:133], 12, v[132:133]
	v_lshl_add_u64 v[130:131], v[130:131], 0, v[138:139]
	v_lshl_add_u64 v[134:135], s[6:7], 0, v[134:135]
	v_lshl_add_u64 v[132:133], s[6:7], 0, v[132:133]
	v_lshl_add_u64 v[134:135], v[134:135], 0, v[138:139]
	v_lshl_add_u64 v[132:133], v[132:133], 0, v[138:139]
	global_load_dwordx4 v[138:141], v[130:131], off offset:16
	global_load_dwordx4 v[142:145], v[130:131], off
	s_mov_b64 s[6:7], 0x80000
	s_waitcnt vmcnt(1)
	v_pk_add_f32 v[122:123], v[122:123], v[138:139]
	s_waitcnt vmcnt(0)
	v_pk_add_f32 v[126:127], v[126:127], v[142:143]
	v_pk_add_f32 v[128:129], v[128:129], v[144:145]
	v_pk_add_f32 v[124:125], v[124:125], v[140:141]
	global_store_dwordx4 v[130:131], v[126:129], off
	global_store_dwordx4 v[130:131], v[122:125], off offset:16
	global_load_dwordx4 v[122:125], v[130:131], off offset:528
	s_nop 0
	global_load_dwordx4 v[126:129], v[130:131], off offset:512
	s_waitcnt vmcnt(1)
	v_pk_add_f32 v[114:115], v[114:115], v[122:123]
	s_waitcnt vmcnt(0)
	v_pk_add_f32 v[118:119], v[118:119], v[126:127]
	v_pk_add_f32 v[120:121], v[120:121], v[128:129]
	v_pk_add_f32 v[116:117], v[116:117], v[124:125]
	global_store_dwordx4 v[130:131], v[118:121], off offset:512
	global_store_dwordx4 v[130:131], v[114:117], off offset:528
	global_load_dwordx4 v[114:117], v[136:137], off offset:16
	s_nop 0
	global_load_dwordx4 v[118:121], v[136:137], off
	s_waitcnt vmcnt(1)
	v_pk_add_f32 v[106:107], v[106:107], v[114:115]
	s_waitcnt vmcnt(0)
	v_pk_add_f32 v[110:111], v[110:111], v[118:119]
	v_pk_add_f32 v[112:113], v[112:113], v[120:121]
	v_pk_add_f32 v[108:109], v[108:109], v[116:117]
	global_store_dwordx4 v[136:137], v[110:113], off
	global_store_dwordx4 v[136:137], v[106:109], off offset:16
	global_load_dwordx4 v[106:109], v[136:137], off offset:528
	s_nop 0
	global_load_dwordx4 v[110:113], v[136:137], off offset:512
	s_waitcnt vmcnt(1)
	v_pk_add_f32 v[98:99], v[98:99], v[106:107]
	s_waitcnt vmcnt(0)
	v_pk_add_f32 v[102:103], v[102:103], v[110:111]
	v_pk_add_f32 v[104:105], v[104:105], v[112:113]
	v_pk_add_f32 v[100:101], v[100:101], v[108:109]
	global_store_dwordx4 v[136:137], v[102:105], off offset:512
	global_store_dwordx4 v[136:137], v[98:101], off offset:528
	global_load_dwordx4 v[100:103], v[134:135], off offset:16
	s_nop 0
	global_load_dwordx4 v[104:107], v[134:135], off
	v_lshl_add_u64 v[108:109], v[130:131], 0, s[6:7]
	s_mov_b64 s[6:7], 0x90000
	v_lshl_add_u64 v[98:99], v[130:131], 0, s[6:7]
	s_mov_b64 s[6:7], 0xa0000
	s_waitcnt vmcnt(1)
	v_pk_add_f32 v[90:91], v[90:91], v[100:101]
	s_waitcnt vmcnt(0)
	v_pk_add_f32 v[94:95], v[94:95], v[104:105]
	v_pk_add_f32 v[96:97], v[96:97], v[106:107]
	v_pk_add_f32 v[92:93], v[92:93], v[102:103]
	global_store_dwordx4 v[134:135], v[94:97], off
	global_store_dwordx4 v[134:135], v[90:93], off offset:16
	global_load_dwordx4 v[90:93], v[134:135], off offset:528
	s_nop 0
	global_load_dwordx4 v[94:97], v[134:135], off offset:512
	s_waitcnt vmcnt(1)
	v_pk_add_f32 v[82:83], v[82:83], v[90:91]
	s_waitcnt vmcnt(0)
	v_pk_add_f32 v[86:87], v[86:87], v[94:95]
	v_pk_add_f32 v[88:89], v[88:89], v[96:97]
	v_pk_add_f32 v[84:85], v[84:85], v[92:93]
	global_store_dwordx4 v[134:135], v[86:89], off offset:512
	global_store_dwordx4 v[134:135], v[82:85], off offset:528
	global_load_dwordx4 v[82:85], v[132:133], off offset:16
	s_nop 0
	global_load_dwordx4 v[86:89], v[132:133], off
	s_waitcnt vmcnt(1)
	v_pk_add_f32 v[26:27], v[26:27], v[82:83]
	s_waitcnt vmcnt(0)
	v_pk_add_f32 v[34:35], v[34:35], v[86:87]
	v_pk_add_f32 v[36:37], v[36:37], v[88:89]
	v_pk_add_f32 v[28:29], v[28:29], v[84:85]
	global_store_dwordx4 v[132:133], v[34:37], off
	global_store_dwordx4 v[132:133], v[26:29], off offset:16
	global_load_dwordx4 v[26:29], v[132:133], off offset:528
	s_nop 0
	global_load_dwordx4 v[34:37], v[132:133], off offset:512
	s_waitcnt vmcnt(1)
	v_pk_add_f32 v[26:27], v[58:59], v[26:27]
	v_pk_add_f32 v[28:29], v[60:61], v[28:29]
	global_store_dwordx4 v[132:133], v[26:29], off offset:528
	s_waitcnt vmcnt(1)
	v_pk_add_f32 v[34:35], v[62:63], v[34:35]
	v_pk_add_f32 v[36:37], v[64:65], v[36:37]
	v_lshl_add_u64 v[28:29], v[130:131], 0, s[6:7]
	s_mov_b64 s[6:7], 0xb0000
	v_lshl_add_u64 v[26:27], v[130:131], 0, s[6:7]
	s_mov_b32 s6, 0x80000
	v_add_co_u32_e32 v62, vcc, s6, v130
	global_store_dwordx4 v[132:133], v[34:37], off offset:512
	s_nop 0
	v_addc_co_u32_e32 v63, vcc, 0, v131, vcc
	global_load_dwordx4 v[34:37], v[62:63], off
	global_load_dwordx4 v[58:61], v[108:109], off offset:16
	s_mov_b32 s6, 0x90000
	s_waitcnt vmcnt(1)
	v_pk_add_f32 v[34:35], v[70:71], v[34:35]
	v_pk_add_f32 v[36:37], v[72:73], v[36:37]
	global_store_dwordx4 v[62:63], v[34:37], off
	v_add_co_u32_e32 v62, vcc, s6, v130
	s_waitcnt vmcnt(1)
	v_pk_add_f32 v[34:35], v[66:67], v[58:59]
	v_pk_add_f32 v[36:37], v[68:69], v[60:61]
	global_store_dwordx4 v[108:109], v[34:37], off offset:16
	global_load_dwordx4 v[34:37], v[108:109], off offset:528
	s_nop 0
	global_load_dwordx4 v[58:61], v[108:109], off offset:512
	v_addc_co_u32_e32 v63, vcc, 0, v131, vcc
	s_mov_b32 s6, 0xa0000
	s_waitcnt vmcnt(1)
	v_pk_add_f32 v[34:35], v[74:75], v[34:35]
	s_waitcnt vmcnt(0)
	v_pk_add_f32 v[58:59], v[78:79], v[58:59]
	v_pk_add_f32 v[60:61], v[80:81], v[60:61]
	v_pk_add_f32 v[36:37], v[76:77], v[36:37]
	global_store_dwordx4 v[108:109], v[58:61], off offset:512
	global_store_dwordx4 v[108:109], v[34:37], off offset:528
	global_load_dwordx4 v[34:37], v[62:63], off
	s_nop 0
	global_load_dwordx4 v[58:61], v[98:99], off offset:16
	s_waitcnt vmcnt(1)
	v_pk_add_f32 v[34:35], v[46:47], v[34:35]
	v_pk_add_f32 v[36:37], v[48:49], v[36:37]
	global_store_dwordx4 v[62:63], v[34:37], off
	v_add_co_u32_e32 v46, vcc, s6, v130
	s_waitcnt vmcnt(1)
	v_pk_add_f32 v[34:35], v[42:43], v[58:59]
	v_pk_add_f32 v[36:37], v[44:45], v[60:61]
	global_store_dwordx4 v[98:99], v[34:37], off offset:16
	global_load_dwordx4 v[34:37], v[98:99], off offset:528
	s_nop 0
	global_load_dwordx4 v[42:45], v[98:99], off offset:512
	v_addc_co_u32_e32 v47, vcc, 0, v131, vcc
	s_mov_b32 s6, 0xb0000
	s_waitcnt vmcnt(1)
	v_pk_add_f32 v[34:35], v[50:51], v[34:35]
	s_waitcnt vmcnt(0)
	v_pk_add_f32 v[42:43], v[54:55], v[42:43]
	v_pk_add_f32 v[44:45], v[56:57], v[44:45]
	v_pk_add_f32 v[36:37], v[52:53], v[36:37]
	global_store_dwordx4 v[98:99], v[42:45], off offset:512
	global_store_dwordx4 v[98:99], v[34:37], off offset:528
	global_load_dwordx4 v[34:37], v[46:47], off
	s_nop 0
	global_load_dwordx4 v[42:45], v[28:29], off offset:16
	s_waitcnt vmcnt(1)
	v_pk_add_f32 v[22:23], v[22:23], v[34:35]
	v_pk_add_f32 v[24:25], v[24:25], v[36:37]
	s_waitcnt vmcnt(0)
	v_pk_add_f32 v[18:19], v[18:19], v[42:43]
	v_pk_add_f32 v[20:21], v[20:21], v[44:45]
	global_store_dwordx4 v[46:47], v[22:25], off
	global_store_dwordx4 v[28:29], v[18:21], off offset:16
	global_load_dwordx4 v[18:21], v[28:29], off offset:528
	s_nop 0
	global_load_dwordx4 v[22:25], v[28:29], off offset:512
	s_waitcnt vmcnt(1)
	v_pk_add_f32 v[18:19], v[30:31], v[18:19]
	s_waitcnt vmcnt(0)
	v_pk_add_f32 v[22:23], v[38:39], v[22:23]
	v_pk_add_f32 v[24:25], v[40:41], v[24:25]
	v_pk_add_f32 v[20:21], v[32:33], v[20:21]
	global_store_dwordx4 v[28:29], v[22:25], off offset:512
	global_store_dwordx4 v[28:29], v[18:21], off offset:528
	v_add_co_u32_e32 v28, vcc, s6, v130
	s_nop 1
	v_addc_co_u32_e32 v29, vcc, 0, v131, vcc
	global_load_dwordx4 v[18:21], v[28:29], off
	global_load_dwordx4 v[22:25], v[26:27], off offset:16
	s_waitcnt vmcnt(1)
	v_pk_add_f32 v[14:15], v[14:15], v[18:19]
	v_pk_add_f32 v[16:17], v[16:17], v[20:21]
	s_waitcnt vmcnt(0)
	v_pk_add_f32 v[10:11], v[10:11], v[22:23]
	v_pk_add_f32 v[12:13], v[12:13], v[24:25]
	global_store_dwordx4 v[28:29], v[14:17], off
	global_store_dwordx4 v[26:27], v[10:13], off offset:16
	global_load_dwordx4 v[10:13], v[26:27], off offset:528
	s_nop 0
	global_load_dwordx4 v[14:17], v[26:27], off offset:512
	s_waitcnt vmcnt(1)
	v_pk_add_f32 v[2:3], v[2:3], v[10:11]
	s_waitcnt vmcnt(0)
	v_pk_add_f32 v[6:7], v[6:7], v[14:15]
	v_pk_add_f32 v[8:9], v[8:9], v[16:17]
	v_pk_add_f32 v[4:5], v[4:5], v[12:13]
	global_store_dwordx4 v[26:27], v[6:9], off offset:512
	global_store_dwordx4 v[26:27], v[2:5], off offset:528

.LBB0_171:
	s_or_b64 exec, exec, s[8:9]
	v_add_u32_e32 v136, s30, v44
	v_lshlrev_b32_e32 v44, 7, v38
	v_and_b32_e32 v45, 7, v38
	v_bitop3_b32 v38, v38, v1, 7 bitop3:0x6c
	v_lshl_or_b32 v38, v38, 4, v44
	v_add_u32_e32 v138, 0, v38
	v_xor_b32_e32 v38, v43, v1
	v_bitop3_b32 v1, v43, v1, 4 bitop3:0x36
	v_lshlrev_b32_e32 v144, 4, v38
	v_lshlrev_b32_e32 v146, 4, v1
	v_xor_b32_e32 v1, 16, v214
	v_add_u32_e32 v38, 64, v39
	v_cmp_lt_i32_e64 s[8:9], v1, v38
	s_lshr_b32 s30, s16, 6
	s_add_i32 s80, s30, -2
	v_cndmask_b32_e64 v1, v214, v1, s[8:9]
	v_lshlrev_b32_e32 v135, 2, v1
	v_xor_b32_e32 v1, 32, v214
	v_cmp_lt_i32_e64 s[8:9], v1, v38
	v_and_b32_e32 v46, 4, v42
	v_lshlrev_b32_e32 v42, 1, v42
	v_cndmask_b32_e64 v1, v214, v1, s[8:9]
	s_add_u32 s8, s20, s13
	s_addc_u32 s9, s21, 0
	v_lshl_add_u64 v[106:107], s[8:9], 0, v[36:37]
	s_and_b32 s8, s52, 15
	v_and_b32_e32 v42, 2, v42
	s_lshl_b32 s8, s8, 7
	v_or_b32_e32 v47, v42, v46
	s_add_u32 s8, s20, s8
	v_bitop3_b32 v42, v42, v45, v46 bitop3:0x36
	v_bitop3_b32 v45, v47, v45, 1 bitop3:0x36
	s_addc_u32 s9, s21, 0
	v_and_b32_e32 v40, 8, v40
	v_lshlrev_b32_e32 v42, 4, v42
	v_lshlrev_b32_e32 v45, 4, v45
	s_add_u32 s8, s8, s12
	v_or3_b32 v42, v42, v44, v40
	v_or3_b32 v40, v45, v44, v40
	s_addc_u32 s9, s9, 0
	v_mov_b32_e32 v46, v0
	v_mov_b32_e32 v47, v0
	v_mov_b32_e32 v48, v0
	v_mov_b32_e32 v49, v0
	v_add_u32_e32 v139, 0, v42
	v_add_u32_e32 v140, 0, v40
	v_lshlrev_b32_e32 v137, 2, v43
	v_lshl_add_u32 v142, v43, 4, 0
	v_lshlrev_b32_e32 v143, 7, v41
	v_or_b32_e32 v148, v136, v41
	v_lshlrev_b32_e32 v101, 2, v1
	v_lshl_add_u64 v[108:109], s[8:9], 0, v[34:35]
	v_mov_b32_e32 v1, v0
	v_mov_b64_e32 v[64:65], v[48:49]
	v_mov_b64_e32 v[42:43], v[46:47]
	v_mov_b64_e32 v[60:61], v[48:49]
	v_mov_b64_e32 v[38:39], v[46:47]
	v_mov_b64_e32 v[56:57], v[48:49]
	v_mov_b64_e32 v[34:35], v[46:47]
	v_mov_b64_e32 v[52:53], v[48:49]
	v_or_b32_e32 v141, 31, v136
	v_add_u32_e32 v145, 0, v144
	v_add_u32_e32 v147, 0, v146
	v_or_b32_e32 v149, 16, v148
	v_add_u32_e32 v150, 0, v143
	v_mov_b32_e32 v99, v0
	v_mov_b32_e32 v110, 0xff800000
	s_mov_b32 s65, 3
	s_movk_i32 s81, 0x7f
	s_xor_b64 s[12:13], vcc, -1
	v_mov_b64_e32 v[62:63], v[46:47]
	v_mov_b64_e32 v[44:45], v[48:49]
	v_mov_b64_e32 v[58:59], v[46:47]
	v_mov_b64_e32 v[40:41], v[48:49]
	v_mov_b64_e32 v[54:55], v[46:47]
	v_mov_b64_e32 v[36:37], v[48:49]
	v_mov_b64_e32 v[50:51], v[46:47]
	v_mov_b32_e32 v111, 0xff800000
	v_mov_b64_e32 v[104:105], v[0:1]
	ds_write_b128 v138, v[2:5] offset:8704
	ds_write_b64 v139, v[6:7] offset:25088
	ds_write_b64 v140, v[8:9] offset:25088
	s_waitcnt lgkmcnt(0)
	s_waitcnt vmcnt(0)
	s_barrier
	s_branch .LBB0_174

.LBB0_174:
	s_add_i32 s82, s65, -1
	s_cmp_ge_u32 s82, s30
	s_cbranch_scc1 .Lattn1_skip1
	v_lshl_add_u64 v[2:3], v[108:109], 0, v[98:99]
	v_add_co_u32_e32 v2, vcc, 0x1b767000, v2
	v_lshl_add_u64 v[6:7], v[106:107], 0, v[98:99]
	v_addc_co_u32_e32 v3, vcc, 0, v3, vcc
	v_add_co_u32_e32 v6, vcc, 0x27b27000, v6
	global_load_dwordx4 v[2:5], v[2:3], off offset:2048
	s_nop 0
	v_addc_co_u32_e32 v7, vcc, 0, v7, vcc
	global_load_dwordx4 v[6:9], v[6:7], off offset:2304
.LBB0_176:
	s_add_i32 s8, s81, 0xffffff81
	v_cmp_le_i32_e32 vcc, s8, v141
	s_and_b64 s[8:9], s[12:13], vcc
	s_and_saveexec_b64 s[16:17], s[8:9]
	s_cbranch_execz .LBB0_180
	v_add_u32_e32 v1, v145, v143
	ds_read_b128 v[66:69], v142
	ds_read_b128 v[70:73], v142 offset:64
	ds_read_b128 v[74:77], v142 offset:128
	ds_read_b128 v[78:81], v142 offset:192
	ds_read_b128 v[82:85], v1 offset:8704
	s_sub_i32 s8, s81, 64
	v_cmp_gt_i32_e32 vcc, s8, v136
	s_waitcnt lgkmcnt(0)
	v_mfma_f32_16x16x32_bf16 v[86:89], v[82:85], v[30:33], v[66:69]
	s_nop 0
	v_mfma_f32_16x16x32_bf16 v[66:69], v[82:85], v[26:29], v[66:69]
	ds_read_b128 v[82:85], v1 offset:10752
	s_waitcnt lgkmcnt(0)
	v_mfma_f32_16x16x32_bf16 v[90:93], v[82:85], v[30:33], v[70:73]
	v_mfma_f32_16x16x32_bf16 v[70:73], v[82:85], v[26:29], v[70:73]
	ds_read_b128 v[82:85], v1 offset:12800
	s_waitcnt lgkmcnt(0)
	v_mfma_f32_16x16x32_bf16 v[94:97], v[82:85], v[30:33], v[74:77]
	v_mfma_f32_16x16x32_bf16 v[112:115], v[82:85], v[26:29], v[74:77]
	s_nop 2
	ds_read_b128 v[74:77], v1 offset:14848
	v_add_u32_e32 v1, v147, v143
	s_waitcnt lgkmcnt(0)
	v_mfma_f32_16x16x32_bf16 v[116:119], v[74:77], v[30:33], v[78:81]
	v_mfma_f32_16x16x32_bf16 v[120:123], v[74:77], v[26:29], v[78:81]
	s_nop 2
	ds_read_b128 v[78:81], v1 offset:8704
	s_waitcnt lgkmcnt(0)
	v_mfma_f32_16x16x32_bf16 v[82:85], v[78:81], v[18:21], v[66:69]
	s_nop 2
	ds_read_b128 v[66:69], v1 offset:10752
	v_mfma_f32_16x16x32_bf16 v[74:77], v[78:81], v[22:25], v[86:89]
	s_waitcnt lgkmcnt(0)
	v_mfma_f32_16x16x32_bf16 v[90:93], v[66:69], v[22:25], v[90:93]
	v_mfma_f32_16x16x32_bf16 v[86:89], v[66:69], v[18:21], v[70:73]
	ds_read_b128 v[66:69], v1 offset:12800
	s_nop 1
	ds_read_b128 v[70:73], v1 offset:14848
	s_waitcnt lgkmcnt(1)
	v_mfma_f32_16x16x32_bf16 v[78:81], v[66:69], v[22:25], v[94:97]
	v_mfma_f32_16x16x32_bf16 v[66:69], v[66:69], v[18:21], v[112:115]
	s_waitcnt lgkmcnt(0)
	v_mfma_f32_16x16x32_bf16 v[94:97], v[70:73], v[22:25], v[116:119]
	v_mfma_f32_16x16x32_bf16 v[70:73], v[70:73], v[18:21], v[120:123]
	s_and_saveexec_b64 s[78:79], vcc
	s_cbranch_execz .LBB0_179
	v_add_u32_e32 v1, s81, v137
	v_add_u32_e32 v113, 0xffffff81, v1
	v_mov_b32_e32 v112, s41
	v_cmp_gt_i32_e32 vcc, v113, v148
	v_cmp_lt_i32_e64 s[8:9], v113, v148
	v_add_u32_e32 v114, 0xffffff83, v1
	v_cndmask_b32_e32 v112, v74, v112, vcc
	v_cndmask_b32_e64 v74, v112, v74, s[8:9]
	v_cndmask_b32_e64 v75, v221, v75, s[8:9]
	v_cmp_le_i32_e64 s[8:9], v114, v148
	v_add_u32_e32 v115, 0xffffff84, v1
	v_mov_b32_e32 v112, s41
	v_cndmask_b32_e64 v76, v221, v76, s[8:9]
	v_cmp_le_i32_e64 s[8:9], v115, v148
	v_add_u32_e32 v116, 0xffffffa4, v1
	s_nop 0
	v_cndmask_b32_e64 v77, v221, v77, s[8:9]
	v_cmp_gt_i32_e64 s[8:9], v113, v149
	s_nop 1
	v_cndmask_b32_e64 v112, v82, v112, s[8:9]
	v_cmp_lt_i32_e64 s[8:9], v113, v149
	v_add_u32_e32 v113, 0xffffff91, v1
	s_nop 0
	v_cndmask_b32_e64 v82, v112, v82, s[8:9]
	v_cndmask_b32_e64 v83, v221, v83, s[8:9]
	v_cmp_le_i32_e64 s[8:9], v114, v149
	v_mov_b32_e32 v112, s41
	v_add_u32_e32 v114, 0xffffff93, v1
	v_cndmask_b32_e64 v84, v221, v84, s[8:9]
	v_cmp_le_i32_e64 s[8:9], v115, v149
	v_cndmask_b32_e32 v86, v86, v112, vcc
	v_add_u32_e32 v115, 0xffffff94, v1
	v_cndmask_b32_e64 v85, v221, v85, s[8:9]
	v_cmp_gt_i32_e64 s[8:9], v113, v148
	v_add_u32_e32 v113, 0xffffff92, v1
	v_cmp_le_i32_e32 vcc, v113, v149
	v_cndmask_b32_e64 v90, v90, v112, s[8:9]
	v_cmp_le_i32_e64 s[8:9], v113, v148
	v_cndmask_b32_e32 v87, v221, v87, vcc
	v_cmp_le_i32_e32 vcc, v114, v149
	v_add_u32_e32 v113, 0xffffffa1, v1
	v_cndmask_b32_e64 v91, v221, v91, s[8:9]
	v_cndmask_b32_e32 v88, v221, v88, vcc
	v_cmp_le_i32_e32 vcc, v115, v149
	v_cmp_le_i32_e64 s[8:9], v114, v148
	v_add_u32_e32 v114, 0xffffffa2, v1
	v_cndmask_b32_e32 v89, v221, v89, vcc
	v_cmp_gt_i32_e32 vcc, v113, v148
	v_cndmask_b32_e64 v92, v221, v92, s[8:9]
	v_cmp_le_i32_e64 s[8:9], v115, v148
	v_cndmask_b32_e32 v78, v78, v112, vcc
	v_cmp_le_i32_e32 vcc, v114, v148
	v_add_u32_e32 v115, 0xffffffa3, v1
	v_cndmask_b32_e64 v93, v221, v93, s[8:9]
	v_cndmask_b32_e32 v79, v221, v79, vcc
	v_cmp_le_i32_e32 vcc, v115, v148
	s_nop 1
	v_cndmask_b32_e32 v80, v221, v80, vcc
	v_cmp_le_i32_e32 vcc, v116, v148
	s_nop 1
	v_cndmask_b32_e32 v81, v221, v81, vcc
	v_cmp_gt_i32_e32 vcc, v113, v149
	v_add_u32_e32 v113, 0xffffffb1, v1
	s_nop 0
	v_cndmask_b32_e32 v66, v66, v112, vcc
	v_cmp_le_i32_e32 vcc, v114, v149
	v_add_u32_e32 v114, 0xffffffb2, v1
	s_nop 0
	v_cndmask_b32_e32 v67, v221, v67, vcc
	v_cmp_le_i32_e32 vcc, v115, v149
	v_add_u32_e32 v115, 0xffffffb3, v1
	v_add_u32_e32 v1, 0xffffffb4, v1
	v_cndmask_b32_e32 v68, v221, v68, vcc
	v_cmp_le_i32_e32 vcc, v116, v149
	s_nop 1
	v_cndmask_b32_e32 v69, v221, v69, vcc
	v_cmp_gt_i32_e32 vcc, v113, v148
	s_nop 1
	v_cndmask_b32_e32 v94, v94, v112, vcc
	v_cmp_le_i32_e32 vcc, v114, v148
	s_nop 1
	v_cndmask_b32_e32 v95, v221, v95, vcc
	v_cmp_le_i32_e32 vcc, v115, v148
	s_nop 1
	v_cndmask_b32_e32 v96, v221, v96, vcc
	v_cmp_le_i32_e32 vcc, v1, v148
	s_nop 1
	v_cndmask_b32_e32 v97, v221, v97, vcc
	v_cmp_gt_i32_e32 vcc, v113, v149
	s_nop 1
	v_cndmask_b32_e32 v70, v70, v112, vcc
	v_cmp_le_i32_e32 vcc, v114, v149
	s_nop 1
	v_cndmask_b32_e32 v71, v221, v71, vcc
	v_cmp_le_i32_e32 vcc, v115, v149
	s_nop 1
	v_cndmask_b32_e32 v72, v221, v72, vcc
	v_cmp_le_i32_e32 vcc, v1, v149
	s_nop 1
	v_cndmask_b32_e32 v73, v221, v73, vcc

.LBB0_180:
	s_or_b64 exec, exec, s[16:17]
	s_add_i32 s16, s65, -2
	s_cmp_lt_u32 s16, s30
	s_cselect_b64 s[8:9], -1, 0
	s_cmp_ge_u32 s16, s30
	s_cbranch_scc1 .LBB0_182
	s_waitcnt vmcnt(2)
	ds_write_b128 v138, v[10:13] offset:16896
	s_nop 0
	ds_write_b64 v139, v[14:15] offset:33280
	ds_write_b64 v140, v[16:17] offset:33280
.LBB0_182:
	s_andn2_b64 vcc, exec, s[8:9]
	s_waitcnt lgkmcnt(0)
	s_barrier
	s_cbranch_vccnz .LBB0_173
	s_cmp_ge_u32 s65, s30
	s_cbranch_scc1 .Lattn1_skip2
	v_lshl_add_u64 v[10:11], v[108:109], 0, v[98:99]
	v_add_co_u32_e32 v10, vcc, 0x1b787000, v10
	v_lshl_add_u64 v[14:15], v[106:107], 0, v[98:99]
	v_addc_co_u32_e32 v11, vcc, 0, v11, vcc
	v_add_co_u32_e32 v14, vcc, 0x27b27000, v14
	global_load_dwordx4 v[10:13], v[10:11], off offset:2048
	s_nop 0
	v_addc_co_u32_e32 v15, vcc, 0, v15, vcc
	global_load_dwordx4 v[14:17], v[14:15], off offset:2432
.LBB0_185:
	s_sub_i32 s8, s81, 63
	v_cmp_le_i32_e32 vcc, s8, v141
	s_and_b64 s[8:9], s[12:13], vcc
	s_and_saveexec_b64 s[16:17], s[8:9]
	s_cbranch_execz .LBB0_189
	v_add_u32_e32 v1, v145, v143
	ds_read_b128 v[66:69], v142 offset:256
	ds_read_b128 v[70:73], v142 offset:320
	ds_read_b128 v[74:77], v142 offset:384
	ds_read_b128 v[78:81], v142 offset:448
	ds_read_b128 v[82:85], v1 offset:16896
	v_cmp_gt_i32_e32 vcc, s81, v136
	s_waitcnt lgkmcnt(0)
	v_mfma_f32_16x16x32_bf16 v[86:89], v[82:85], v[30:33], v[66:69]
	s_nop 0
	v_mfma_f32_16x16x32_bf16 v[82:85], v[82:85], v[26:29], v[66:69]
	s_nop 2
	ds_read_b128 v[66:69], v1 offset:18944
	s_waitcnt lgkmcnt(0)
	v_mfma_f32_16x16x32_bf16 v[90:93], v[66:69], v[30:33], v[70:73]
	v_mfma_f32_16x16x32_bf16 v[70:73], v[66:69], v[26:29], v[70:73]
	ds_read_b128 v[66:69], v1 offset:20992
	s_waitcnt lgkmcnt(0)
	v_mfma_f32_16x16x32_bf16 v[94:97], v[66:69], v[30:33], v[74:77]
	v_mfma_f32_16x16x32_bf16 v[112:115], v[66:69], v[26:29], v[74:77]
	ds_read_b128 v[66:69], v1 offset:23040
	v_add_u32_e32 v1, v147, v143
	s_nop 0
	ds_read_b128 v[74:77], v1 offset:16896
	s_waitcnt lgkmcnt(1)
	v_mfma_f32_16x16x32_bf16 v[116:119], v[66:69], v[30:33], v[78:81]
	v_mfma_f32_16x16x32_bf16 v[78:81], v[66:69], v[26:29], v[78:81]
	s_waitcnt lgkmcnt(0)
	v_mfma_f32_16x16x32_bf16 v[66:69], v[74:77], v[22:25], v[86:89]
	s_nop 0
	v_mfma_f32_16x16x32_bf16 v[86:89], v[74:77], v[18:21], v[82:85]
	ds_read_b128 v[74:77], v1 offset:18944
	s_waitcnt lgkmcnt(0)
	v_mfma_f32_16x16x32_bf16 v[90:93], v[74:77], v[22:25], v[90:93]
	v_mfma_f32_16x16x32_bf16 v[74:77], v[74:77], v[18:21], v[70:73]
	s_nop 2
	ds_read_b128 v[70:73], v1 offset:20992
	s_waitcnt lgkmcnt(0)
	v_mfma_f32_16x16x32_bf16 v[82:85], v[70:73], v[22:25], v[94:97]
	v_mfma_f32_16x16x32_bf16 v[70:73], v[70:73], v[18:21], v[112:115]
	s_nop 2
	ds_read_b128 v[112:115], v1 offset:23040
	s_waitcnt lgkmcnt(0)
	v_mfma_f32_16x16x32_bf16 v[94:97], v[112:115], v[22:25], v[116:119]
	v_mfma_f32_16x16x32_bf16 v[78:81], v[112:115], v[18:21], v[78:81]
	s_and_saveexec_b64 s[78:79], vcc
	s_cbranch_execz .LBB0_188
	v_add_u32_e32 v1, s81, v137
	v_subrev_u32_e32 v113, 63, v1
	v_mov_b32_e32 v112, s41
	v_cmp_gt_i32_e32 vcc, v113, v148
	v_cmp_lt_i32_e64 s[8:9], v113, v148
	v_subrev_u32_e32 v114, 61, v1
	v_cndmask_b32_e32 v112, v66, v112, vcc
	v_cndmask_b32_e64 v66, v112, v66, s[8:9]
	v_cndmask_b32_e64 v67, v221, v67, s[8:9]
	v_cmp_le_i32_e64 s[8:9], v114, v148
	v_subrev_u32_e32 v115, 60, v1
	v_mov_b32_e32 v112, s41
	v_cndmask_b32_e64 v68, v221, v68, s[8:9]
	v_cmp_le_i32_e64 s[8:9], v115, v148
	v_subrev_u32_e32 v116, 28, v1
	s_nop 0
	v_cndmask_b32_e64 v69, v221, v69, s[8:9]
	v_cmp_gt_i32_e64 s[8:9], v113, v149
	s_nop 1
	v_cndmask_b32_e64 v112, v86, v112, s[8:9]
	v_cmp_lt_i32_e64 s[8:9], v113, v149
	v_subrev_u32_e32 v113, 47, v1
	s_nop 0
	v_cndmask_b32_e64 v86, v112, v86, s[8:9]
	v_cndmask_b32_e64 v87, v221, v87, s[8:9]
	v_cmp_le_i32_e64 s[8:9], v114, v149
	v_mov_b32_e32 v112, s41
	v_subrev_u32_e32 v114, 45, v1
	v_cndmask_b32_e64 v88, v221, v88, s[8:9]
	v_cmp_le_i32_e64 s[8:9], v115, v149
	v_cndmask_b32_e32 v74, v74, v112, vcc
	v_subrev_u32_e32 v115, 44, v1
	v_cndmask_b32_e64 v89, v221, v89, s[8:9]
	v_cmp_gt_i32_e64 s[8:9], v113, v148
	v_subrev_u32_e32 v113, 46, v1
	v_cmp_le_i32_e32 vcc, v113, v149
	v_cndmask_b32_e64 v90, v90, v112, s[8:9]
	v_cmp_le_i32_e64 s[8:9], v113, v148
	v_cndmask_b32_e32 v75, v221, v75, vcc
	v_cmp_le_i32_e32 vcc, v114, v149
	v_subrev_u32_e32 v113, 31, v1
	v_cndmask_b32_e64 v91, v221, v91, s[8:9]
	v_cndmask_b32_e32 v76, v221, v76, vcc
	v_cmp_le_i32_e32 vcc, v115, v149
	v_cmp_le_i32_e64 s[8:9], v114, v148
	v_subrev_u32_e32 v114, 30, v1
	v_cndmask_b32_e32 v77, v221, v77, vcc
	v_cmp_gt_i32_e32 vcc, v113, v148
	v_cndmask_b32_e64 v92, v221, v92, s[8:9]
	v_cmp_le_i32_e64 s[8:9], v115, v148
	v_cndmask_b32_e32 v82, v82, v112, vcc
	v_cmp_le_i32_e32 vcc, v114, v148
	v_subrev_u32_e32 v115, 29, v1
	v_cndmask_b32_e64 v93, v221, v93, s[8:9]
	v_cndmask_b32_e32 v83, v221, v83, vcc
	v_cmp_le_i32_e32 vcc, v115, v148
	s_nop 1
	v_cndmask_b32_e32 v84, v221, v84, vcc
	v_cmp_le_i32_e32 vcc, v116, v148
	s_nop 1
	v_cndmask_b32_e32 v85, v221, v85, vcc
	v_cmp_gt_i32_e32 vcc, v113, v149
	v_add_u32_e32 v113, -15, v1
	s_nop 0
	v_cndmask_b32_e32 v70, v70, v112, vcc
	v_cmp_le_i32_e32 vcc, v114, v149
	v_add_u32_e32 v114, -14, v1
	s_nop 0
	v_cndmask_b32_e32 v71, v221, v71, vcc
	v_cmp_le_i32_e32 vcc, v115, v149
	v_add_u32_e32 v115, -13, v1
	v_add_u32_e32 v1, -12, v1
	v_cndmask_b32_e32 v72, v221, v72, vcc
	v_cmp_le_i32_e32 vcc, v116, v149
	s_nop 1
	v_cndmask_b32_e32 v73, v221, v73, vcc
	v_cmp_gt_i32_e32 vcc, v113, v148
	s_nop 1
	v_cndmask_b32_e32 v94, v94, v112, vcc
	v_cmp_le_i32_e32 vcc, v114, v148
	s_nop 1
	v_cndmask_b32_e32 v95, v221, v95, vcc
	v_cmp_le_i32_e32 vcc, v115, v148
	s_nop 1
	v_cndmask_b32_e32 v96, v221, v96, vcc
	v_cmp_le_i32_e32 vcc, v1, v148
	s_nop 1
	v_cndmask_b32_e32 v97, v221, v97, vcc
	v_cmp_gt_i32_e32 vcc, v113, v149
	s_nop 1
	v_cndmask_b32_e32 v78, v78, v112, vcc
	v_cmp_le_i32_e32 vcc, v114, v149
	s_nop 1
	v_cndmask_b32_e32 v79, v221, v79, vcc
	v_cmp_le_i32_e32 vcc, v115, v149
	s_nop 1
	v_cndmask_b32_e32 v80, v221, v80, vcc
	v_cmp_le_i32_e32 vcc, v1, v149
	s_nop 1
	v_cndmask_b32_e32 v81, v221, v81, vcc

.LBB0_189:
	s_or_b64 exec, exec, s[16:17]
	s_add_i32 s8, s65, -3
	s_cmp_ge_u32 s8, s80
	s_cbranch_scc1 .LBB0_172
	s_waitcnt vmcnt(2)
	ds_write_b128 v138, v[2:5] offset:8704
	s_nop 0
	ds_write_b64 v139, v[6:7] offset:25088
	ds_write_b64 v140, v[8:9] offset:25088
	s_branch .LBB0_172
.Lattn1_skip1:
	s_waitcnt vmcnt(0)
	s_branch .LBB0_176

.LBB0_203:
	s_or_b64 exec, exec, s[8:9]
	v_lshlrev_b32_e32 v45, 7, v36
	v_and_b32_e32 v46, 7, v36
	v_bitop3_b32 v36, v36, v1, 7 bitop3:0x6c
	v_lshl_or_b32 v36, v36, 4, v45
	v_add_u32_e32 v138, 0, v36
	v_xor_b32_e32 v36, v43, v1
	v_bitop3_b32 v1, v43, v1, 4 bitop3:0x36
	v_lshlrev_b32_e32 v144, 4, v36
	v_lshlrev_b32_e32 v146, 4, v1
	v_xor_b32_e32 v1, 16, v214
	v_add_u32_e32 v36, 64, v37
	v_cmp_lt_i32_e64 s[8:9], v1, v36
	v_and_b32_e32 v47, 4, v42
	v_lshlrev_b32_e32 v42, 1, v42
	v_cndmask_b32_e64 v1, v214, v1, s[8:9]
	v_lshlrev_b32_e32 v135, 2, v1
	v_xor_b32_e32 v1, 32, v214
	v_cmp_lt_i32_e64 s[8:9], v1, v36
	v_and_b32_e32 v42, 2, v42
	v_or_b32_e32 v48, v42, v47
	v_cndmask_b32_e64 v1, v214, v1, s[8:9]
	s_add_u32 s8, s20, s17
	s_addc_u32 s9, s21, s16
	v_lshl_add_u64 v[106:107], s[8:9], 0, v[40:41]
	s_and_b32 s8, s52, 15
	s_lshl_b32 s8, s8, 7
	s_add_u32 s8, s20, s8
	v_bitop3_b32 v42, v42, v46, v47 bitop3:0x36
	v_bitop3_b32 v46, v48, v46, 1 bitop3:0x36
	s_addc_u32 s9, s21, 0
	v_and_b32_e32 v38, 8, v38
	v_lshlrev_b32_e32 v42, 4, v42
	v_lshlrev_b32_e32 v46, 4, v46
	s_add_u32 s8, s8, s12
	v_add_u32_e32 v136, 0x400, v44
	v_or3_b32 v42, v42, v45, v38
	v_or3_b32 v38, v46, v45, v38
	s_addc_u32 s9, s9, s13
	v_mov_b32_e32 v46, v0
	v_mov_b32_e32 v47, v0
	v_mov_b32_e32 v48, v0
	v_mov_b32_e32 v49, v0
	v_add_u32_e32 v139, 0, v42
	v_add_u32_e32 v140, 0, v38
	v_add_u32_e32 v141, 0x41f, v44
	v_lshlrev_b32_e32 v137, 2, v43
	v_lshl_add_u32 v142, v43, 4, 0
	v_lshlrev_b32_e32 v143, 7, v39
	v_or_b32_e32 v148, v136, v39
	v_lshlrev_b32_e32 v101, 2, v1
	v_add_u32_e32 v151, 0x3c1, v44
	v_lshl_add_u64 v[108:109], s[8:9], 0, v[34:35]
	v_mov_b32_e32 v1, v0
	v_mov_b64_e32 v[64:65], v[48:49]
	v_mov_b64_e32 v[42:43], v[46:47]
	v_mov_b64_e32 v[60:61], v[48:49]
	v_mov_b64_e32 v[38:39], v[46:47]
	v_mov_b64_e32 v[56:57], v[48:49]
	v_mov_b64_e32 v[34:35], v[46:47]
	v_mov_b64_e32 v[52:53], v[48:49]
	v_add_u32_e32 v145, 0, v144
	v_add_u32_e32 v147, 0, v146
	v_or_b32_e32 v149, 16, v148
	v_add_u32_e32 v150, 0, v143
	v_mov_b32_e32 v99, v0
	v_mov_b32_e32 v110, 0xff800000
	s_mov_b32 s30, 0
	s_movk_i32 s65, 0x7f
	s_xor_b64 s[12:13], vcc, -1
	v_mov_b64_e32 v[62:63], v[46:47]
	v_mov_b64_e32 v[44:45], v[48:49]
	v_mov_b64_e32 v[58:59], v[46:47]
	v_mov_b64_e32 v[40:41], v[48:49]
	v_mov_b64_e32 v[54:55], v[46:47]
	v_mov_b64_e32 v[36:37], v[48:49]
	v_mov_b64_e32 v[50:51], v[46:47]
	v_mov_b32_e32 v111, 0xff800000
	v_mov_b64_e32 v[104:105], v[0:1]
	ds_write_b128 v138, v[2:5] offset:8704
	ds_write_b64 v139, v[6:7] offset:25088
	ds_write_b64 v140, v[8:9] offset:25088
	s_waitcnt lgkmcnt(0)
	s_waitcnt vmcnt(0)
	s_barrier
	s_branch .LBB0_206

.LBB0_206:
	s_cmp_lt_u32 s30, 15
	s_cselect_b64 s[78:79], -1, 0
	s_cmp_gt_u32 s30, 14
	s_cselect_b64 s[16:17], -1, 0
	s_and_b64 vcc, exec, s[16:17]
	s_cbranch_vccnz .Lattn2_skip1
	v_lshl_add_u64 v[2:3], v[108:109], 0, v[98:99]
	v_add_co_u32_e32 v2, vcc, 0x1b767000, v2
	v_lshl_add_u64 v[6:7], v[106:107], 0, v[98:99]
	v_addc_co_u32_e32 v3, vcc, 0, v3, vcc
	v_add_co_u32_e32 v6, vcc, 0x2fb27000, v6
	global_load_dwordx4 v[2:5], v[2:3], off offset:2048
	s_nop 0
	v_addc_co_u32_e32 v7, vcc, 0, v7, vcc
	global_load_dwordx4 v[6:9], v[6:7], off offset:2304
.LBB0_208:
	s_add_i32 s8, s65, 0xffffff81
	v_cmp_le_i32_e32 vcc, s8, v141
	s_and_b64 s[82:83], s[12:13], vcc
	s_and_saveexec_b64 s[80:81], s[82:83]
	s_cbranch_execz .LBB0_212
	v_add_u32_e32 v1, v145, v143
	ds_read_b128 v[66:69], v142
	ds_read_b128 v[70:73], v142 offset:64
	ds_read_b128 v[74:77], v142 offset:128
	ds_read_b128 v[78:81], v142 offset:192
	ds_read_b128 v[82:85], v1 offset:8704
	v_cmp_gt_i32_e32 vcc, s8, v151
	s_waitcnt lgkmcnt(0)
	v_mfma_f32_16x16x32_bf16 v[86:89], v[82:85], v[30:33], v[66:69]
	s_nop 0
	v_mfma_f32_16x16x32_bf16 v[66:69], v[82:85], v[26:29], v[66:69]
	ds_read_b128 v[82:85], v1 offset:10752
	s_waitcnt lgkmcnt(0)
	v_mfma_f32_16x16x32_bf16 v[90:93], v[82:85], v[30:33], v[70:73]
	v_mfma_f32_16x16x32_bf16 v[70:73], v[82:85], v[26:29], v[70:73]
	ds_read_b128 v[82:85], v1 offset:12800
	s_waitcnt lgkmcnt(0)
	v_mfma_f32_16x16x32_bf16 v[94:97], v[82:85], v[30:33], v[74:77]
	v_mfma_f32_16x16x32_bf16 v[112:115], v[82:85], v[26:29], v[74:77]
	s_nop 2
	ds_read_b128 v[74:77], v1 offset:14848
	v_add_u32_e32 v1, v147, v143
	s_waitcnt lgkmcnt(0)
	v_mfma_f32_16x16x32_bf16 v[116:119], v[74:77], v[30:33], v[78:81]
	v_mfma_f32_16x16x32_bf16 v[120:123], v[74:77], v[26:29], v[78:81]
	s_nop 2
	ds_read_b128 v[78:81], v1 offset:8704
	s_waitcnt lgkmcnt(0)
	v_mfma_f32_16x16x32_bf16 v[82:85], v[78:81], v[18:21], v[66:69]
	s_nop 2
	ds_read_b128 v[66:69], v1 offset:10752
	v_mfma_f32_16x16x32_bf16 v[74:77], v[78:81], v[22:25], v[86:89]
	s_waitcnt lgkmcnt(0)
	v_mfma_f32_16x16x32_bf16 v[90:93], v[66:69], v[22:25], v[90:93]
	v_mfma_f32_16x16x32_bf16 v[86:89], v[66:69], v[18:21], v[70:73]
	ds_read_b128 v[66:69], v1 offset:12800
	s_nop 1
	ds_read_b128 v[70:73], v1 offset:14848
	s_waitcnt lgkmcnt(1)
	v_mfma_f32_16x16x32_bf16 v[78:81], v[66:69], v[22:25], v[94:97]
	v_mfma_f32_16x16x32_bf16 v[66:69], v[66:69], v[18:21], v[112:115]
	s_waitcnt lgkmcnt(0)
	v_mfma_f32_16x16x32_bf16 v[94:97], v[70:73], v[22:25], v[116:119]
	v_mfma_f32_16x16x32_bf16 v[70:73], v[70:73], v[18:21], v[120:123]
	s_and_saveexec_b64 s[82:83], vcc
	s_cbranch_execz .LBB0_211
	v_add_u32_e32 v1, s65, v137
	v_add_u32_e32 v113, 0xffffff81, v1
	v_mov_b32_e32 v112, s41
	v_cmp_gt_i32_e32 vcc, v113, v148
	v_cmp_lt_i32_e64 s[8:9], v113, v148
	v_add_u32_e32 v114, 0xffffff83, v1
	v_cndmask_b32_e32 v112, v74, v112, vcc
	v_cndmask_b32_e64 v74, v112, v74, s[8:9]
	v_cndmask_b32_e64 v75, v221, v75, s[8:9]
	v_cmp_le_i32_e64 s[8:9], v114, v148
	v_add_u32_e32 v115, 0xffffff84, v1
	v_mov_b32_e32 v112, s41
	v_cndmask_b32_e64 v76, v221, v76, s[8:9]
	v_cmp_le_i32_e64 s[8:9], v115, v148
	v_add_u32_e32 v116, 0xffffffa4, v1
	s_nop 0
	v_cndmask_b32_e64 v77, v221, v77, s[8:9]
	v_cmp_gt_i32_e64 s[8:9], v113, v149
	s_nop 1
	v_cndmask_b32_e64 v112, v82, v112, s[8:9]
	v_cmp_lt_i32_e64 s[8:9], v113, v149
	v_add_u32_e32 v113, 0xffffff91, v1
	s_nop 0
	v_cndmask_b32_e64 v82, v112, v82, s[8:9]
	v_cndmask_b32_e64 v83, v221, v83, s[8:9]
	v_cmp_le_i32_e64 s[8:9], v114, v149
	v_mov_b32_e32 v112, s41
	v_add_u32_e32 v114, 0xffffff93, v1
	v_cndmask_b32_e64 v84, v221, v84, s[8:9]
	v_cmp_le_i32_e64 s[8:9], v115, v149
	v_cndmask_b32_e32 v86, v86, v112, vcc
	v_add_u32_e32 v115, 0xffffff94, v1
	v_cndmask_b32_e64 v85, v221, v85, s[8:9]
	v_cmp_gt_i32_e64 s[8:9], v113, v148
	v_add_u32_e32 v113, 0xffffff92, v1
	v_cmp_le_i32_e32 vcc, v113, v149
	v_cndmask_b32_e64 v90, v90, v112, s[8:9]
	v_cmp_le_i32_e64 s[8:9], v113, v148
	v_cndmask_b32_e32 v87, v221, v87, vcc
	v_cmp_le_i32_e32 vcc, v114, v149
	v_add_u32_e32 v113, 0xffffffa1, v1
	v_cndmask_b32_e64 v91, v221, v91, s[8:9]
	v_cndmask_b32_e32 v88, v221, v88, vcc
	v_cmp_le_i32_e32 vcc, v115, v149
	v_cmp_le_i32_e64 s[8:9], v114, v148
	v_add_u32_e32 v114, 0xffffffa2, v1
	v_cndmask_b32_e32 v89, v221, v89, vcc
	v_cmp_gt_i32_e32 vcc, v113, v148
	v_cndmask_b32_e64 v92, v221, v92, s[8:9]
	v_cmp_le_i32_e64 s[8:9], v115, v148
	v_cndmask_b32_e32 v78, v78, v112, vcc
	v_cmp_le_i32_e32 vcc, v114, v148
	v_add_u32_e32 v115, 0xffffffa3, v1
	v_cndmask_b32_e64 v93, v221, v93, s[8:9]
	v_cndmask_b32_e32 v79, v221, v79, vcc
	v_cmp_le_i32_e32 vcc, v115, v148
	s_nop 1
	v_cndmask_b32_e32 v80, v221, v80, vcc
	v_cmp_le_i32_e32 vcc, v116, v148
	s_nop 1
	v_cndmask_b32_e32 v81, v221, v81, vcc
	v_cmp_gt_i32_e32 vcc, v113, v149
	v_add_u32_e32 v113, 0xffffffb1, v1
	s_nop 0
	v_cndmask_b32_e32 v66, v66, v112, vcc
	v_cmp_le_i32_e32 vcc, v114, v149
	v_add_u32_e32 v114, 0xffffffb2, v1
	s_nop 0
	v_cndmask_b32_e32 v67, v221, v67, vcc
	v_cmp_le_i32_e32 vcc, v115, v149
	v_add_u32_e32 v115, 0xffffffb3, v1
	v_add_u32_e32 v1, 0xffffffb4, v1
	v_cndmask_b32_e32 v68, v221, v68, vcc
	v_cmp_le_i32_e32 vcc, v116, v149
	s_nop 1
	v_cndmask_b32_e32 v69, v221, v69, vcc
	v_cmp_gt_i32_e32 vcc, v113, v148
	s_nop 1
	v_cndmask_b32_e32 v94, v94, v112, vcc
	v_cmp_le_i32_e32 vcc, v114, v148
	s_nop 1
	v_cndmask_b32_e32 v95, v221, v95, vcc
	v_cmp_le_i32_e32 vcc, v115, v148
	s_nop 1
	v_cndmask_b32_e32 v96, v221, v96, vcc
	v_cmp_le_i32_e32 vcc, v1, v148
	s_nop 1
	v_cndmask_b32_e32 v97, v221, v97, vcc
	v_cmp_gt_i32_e32 vcc, v113, v149
	s_nop 1
	v_cndmask_b32_e32 v70, v70, v112, vcc
	v_cmp_le_i32_e32 vcc, v114, v149
	s_nop 1
	v_cndmask_b32_e32 v71, v221, v71, vcc
	v_cmp_le_i32_e32 vcc, v115, v149
	s_nop 1
	v_cndmask_b32_e32 v72, v221, v72, vcc
	v_cmp_le_i32_e32 vcc, v1, v149
	s_nop 1
	v_cndmask_b32_e32 v73, v221, v73, vcc

.LBB0_212:
	s_or_b64 exec, exec, s[80:81]
	s_add_i32 s34, s30, 1
	s_cmp_lt_u32 s34, 17
	s_cselect_b64 s[8:9], -1, 0
	s_cmp_gt_u32 s34, 16
	s_cbranch_scc1 .LBB0_214
	s_waitcnt vmcnt(2)
	ds_write_b128 v138, v[10:13] offset:16896
	s_nop 0
	ds_write_b64 v139, v[14:15] offset:33280
	ds_write_b64 v140, v[16:17] offset:33280
.LBB0_214:
	s_andn2_b64 vcc, exec, s[8:9]
	s_waitcnt lgkmcnt(0)
	s_barrier
	s_cbranch_vccnz .LBB0_205
	s_cmp_gt_u32 s30, 13
	s_cbranch_scc1 .Lattn2_skip2
	v_lshl_add_u64 v[10:11], v[108:109], 0, v[98:99]
	v_add_co_u32_e32 v10, vcc, 0x1b787000, v10
	v_lshl_add_u64 v[14:15], v[106:107], 0, v[98:99]
	v_addc_co_u32_e32 v11, vcc, 0, v11, vcc
	v_add_co_u32_e32 v14, vcc, 0x2fb27000, v14
	global_load_dwordx4 v[10:13], v[10:11], off offset:2048
	s_nop 0
	v_addc_co_u32_e32 v15, vcc, 0, v15, vcc
	global_load_dwordx4 v[14:17], v[14:15], off offset:2432
.LBB0_217:
	s_sub_i32 s8, s65, 63
	v_cmp_le_i32_e32 vcc, s8, v141
	s_and_b64 s[8:9], s[12:13], vcc
	s_and_saveexec_b64 s[80:81], s[8:9]
	s_cbranch_execz .LBB0_221
	v_add_u32_e32 v1, v145, v143
	ds_read_b128 v[66:69], v142 offset:256
	ds_read_b128 v[70:73], v142 offset:320
	ds_read_b128 v[74:77], v142 offset:384
	ds_read_b128 v[78:81], v142 offset:448
	ds_read_b128 v[82:85], v1 offset:16896
	v_cmp_gt_u32_e32 vcc, s65, v136
	s_waitcnt lgkmcnt(0)
	v_mfma_f32_16x16x32_bf16 v[86:89], v[82:85], v[30:33], v[66:69]
	s_nop 0
	v_mfma_f32_16x16x32_bf16 v[82:85], v[82:85], v[26:29], v[66:69]
	s_nop 2
	ds_read_b128 v[66:69], v1 offset:18944
	s_waitcnt lgkmcnt(0)
	v_mfma_f32_16x16x32_bf16 v[90:93], v[66:69], v[30:33], v[70:73]
	v_mfma_f32_16x16x32_bf16 v[70:73], v[66:69], v[26:29], v[70:73]
	ds_read_b128 v[66:69], v1 offset:20992
	s_waitcnt lgkmcnt(0)
	v_mfma_f32_16x16x32_bf16 v[94:97], v[66:69], v[30:33], v[74:77]
	v_mfma_f32_16x16x32_bf16 v[112:115], v[66:69], v[26:29], v[74:77]
	ds_read_b128 v[66:69], v1 offset:23040
	v_add_u32_e32 v1, v147, v143
	s_nop 0
	ds_read_b128 v[74:77], v1 offset:16896
	s_waitcnt lgkmcnt(1)
	v_mfma_f32_16x16x32_bf16 v[116:119], v[66:69], v[30:33], v[78:81]
	v_mfma_f32_16x16x32_bf16 v[78:81], v[66:69], v[26:29], v[78:81]
	s_waitcnt lgkmcnt(0)
	v_mfma_f32_16x16x32_bf16 v[66:69], v[74:77], v[22:25], v[86:89]
	s_nop 0
	v_mfma_f32_16x16x32_bf16 v[86:89], v[74:77], v[18:21], v[82:85]
	ds_read_b128 v[74:77], v1 offset:18944
	s_waitcnt lgkmcnt(0)
	v_mfma_f32_16x16x32_bf16 v[90:93], v[74:77], v[22:25], v[90:93]
	v_mfma_f32_16x16x32_bf16 v[74:77], v[74:77], v[18:21], v[70:73]
	s_nop 2
	ds_read_b128 v[70:73], v1 offset:20992
	s_waitcnt lgkmcnt(0)
	v_mfma_f32_16x16x32_bf16 v[82:85], v[70:73], v[22:25], v[94:97]
	v_mfma_f32_16x16x32_bf16 v[70:73], v[70:73], v[18:21], v[112:115]
	s_nop 2
	ds_read_b128 v[112:115], v1 offset:23040
	s_waitcnt lgkmcnt(0)
	v_mfma_f32_16x16x32_bf16 v[94:97], v[112:115], v[22:25], v[116:119]
	v_mfma_f32_16x16x32_bf16 v[78:81], v[112:115], v[18:21], v[78:81]
	s_and_saveexec_b64 s[82:83], vcc
	s_cbranch_execz .LBB0_220
	v_add_u32_e32 v1, s65, v137
	v_subrev_u32_e32 v113, 63, v1
	v_mov_b32_e32 v112, s41
	v_cmp_gt_i32_e32 vcc, v113, v148
	v_cmp_lt_i32_e64 s[8:9], v113, v148
	v_subrev_u32_e32 v114, 61, v1
	v_cndmask_b32_e32 v112, v66, v112, vcc
	v_cndmask_b32_e64 v66, v112, v66, s[8:9]
	v_cndmask_b32_e64 v67, v221, v67, s[8:9]
	v_cmp_le_i32_e64 s[8:9], v114, v148
	v_subrev_u32_e32 v115, 60, v1
	v_mov_b32_e32 v112, s41
	v_cndmask_b32_e64 v68, v221, v68, s[8:9]
	v_cmp_le_i32_e64 s[8:9], v115, v148
	v_subrev_u32_e32 v116, 28, v1
	s_nop 0
	v_cndmask_b32_e64 v69, v221, v69, s[8:9]
	v_cmp_gt_i32_e64 s[8:9], v113, v149
	s_nop 1
	v_cndmask_b32_e64 v112, v86, v112, s[8:9]
	v_cmp_lt_i32_e64 s[8:9], v113, v149
	v_subrev_u32_e32 v113, 47, v1
	s_nop 0
	v_cndmask_b32_e64 v86, v112, v86, s[8:9]
	v_cndmask_b32_e64 v87, v221, v87, s[8:9]
	v_cmp_le_i32_e64 s[8:9], v114, v149
	v_mov_b32_e32 v112, s41
	v_subrev_u32_e32 v114, 45, v1
	v_cndmask_b32_e64 v88, v221, v88, s[8:9]
	v_cmp_le_i32_e64 s[8:9], v115, v149
	v_cndmask_b32_e32 v74, v74, v112, vcc
	v_subrev_u32_e32 v115, 44, v1
	v_cndmask_b32_e64 v89, v221, v89, s[8:9]
	v_cmp_gt_i32_e64 s[8:9], v113, v148
	v_subrev_u32_e32 v113, 46, v1
	v_cmp_le_i32_e32 vcc, v113, v149
	v_cndmask_b32_e64 v90, v90, v112, s[8:9]
	v_cmp_le_i32_e64 s[8:9], v113, v148
	v_cndmask_b32_e32 v75, v221, v75, vcc
	v_cmp_le_i32_e32 vcc, v114, v149
	v_subrev_u32_e32 v113, 31, v1
	v_cndmask_b32_e64 v91, v221, v91, s[8:9]
	v_cndmask_b32_e32 v76, v221, v76, vcc
	v_cmp_le_i32_e32 vcc, v115, v149
	v_cmp_le_i32_e64 s[8:9], v114, v148
	v_subrev_u32_e32 v114, 30, v1
	v_cndmask_b32_e32 v77, v221, v77, vcc
	v_cmp_gt_i32_e32 vcc, v113, v148
	v_cndmask_b32_e64 v92, v221, v92, s[8:9]
	v_cmp_le_i32_e64 s[8:9], v115, v148
	v_cndmask_b32_e32 v82, v82, v112, vcc
	v_cmp_le_i32_e32 vcc, v114, v148
	v_subrev_u32_e32 v115, 29, v1
	v_cndmask_b32_e64 v93, v221, v93, s[8:9]
	v_cndmask_b32_e32 v83, v221, v83, vcc
	v_cmp_le_i32_e32 vcc, v115, v148
	s_nop 1
	v_cndmask_b32_e32 v84, v221, v84, vcc
	v_cmp_le_i32_e32 vcc, v116, v148
	s_nop 1
	v_cndmask_b32_e32 v85, v221, v85, vcc
	v_cmp_gt_i32_e32 vcc, v113, v149
	v_add_u32_e32 v113, -15, v1
	s_nop 0
	v_cndmask_b32_e32 v70, v70, v112, vcc
	v_cmp_le_i32_e32 vcc, v114, v149
	v_add_u32_e32 v114, -14, v1
	s_nop 0
	v_cndmask_b32_e32 v71, v221, v71, vcc
	v_cmp_le_i32_e32 vcc, v115, v149
	v_add_u32_e32 v115, -13, v1
	v_add_u32_e32 v1, -12, v1
	v_cndmask_b32_e32 v72, v221, v72, vcc
	v_cmp_le_i32_e32 vcc, v116, v149
	s_nop 1
	v_cndmask_b32_e32 v73, v221, v73, vcc
	v_cmp_gt_i32_e32 vcc, v113, v148
	s_nop 1
	v_cndmask_b32_e32 v94, v94, v112, vcc
	v_cmp_le_i32_e32 vcc, v114, v148
	s_nop 1
	v_cndmask_b32_e32 v95, v221, v95, vcc
	v_cmp_le_i32_e32 vcc, v115, v148
	s_nop 1
	v_cndmask_b32_e32 v96, v221, v96, vcc
	v_cmp_le_i32_e32 vcc, v1, v148
	s_nop 1
	v_cndmask_b32_e32 v97, v221, v97, vcc
	v_cmp_gt_i32_e32 vcc, v113, v149
	s_nop 1
	v_cndmask_b32_e32 v78, v78, v112, vcc
	v_cmp_le_i32_e32 vcc, v114, v149
	s_nop 1
	v_cndmask_b32_e32 v79, v221, v79, vcc
	v_cmp_le_i32_e32 vcc, v115, v149
	s_nop 1
	v_cndmask_b32_e32 v80, v221, v80, vcc
	v_cmp_le_i32_e32 vcc, v1, v149
	s_nop 1
	v_cndmask_b32_e32 v81, v221, v81, vcc

.LBB0_221:
	s_or_b64 exec, exec, s[80:81]
	s_andn2_b64 vcc, exec, s[78:79]
	s_cbranch_vccnz .LBB0_204
	s_waitcnt vmcnt(2)
	ds_write_b128 v138, v[2:5] offset:8704
	s_nop 0
	ds_write_b64 v139, v[6:7] offset:25088
	ds_write_b64 v140, v[8:9] offset:25088
	s_branch .LBB0_204

.LBB0_273:
	s_or_b64 exec, exec, s[8:9]
	s_waitcnt vmcnt(10)
	v_mul_f32_e32 v1, 0xbfb8aa3b, v76
	v_exp_f32_e32 v1, v1
	s_lshl_b32 s8, s11, 1
	s_add_u32 s8, s56, s8
	s_addc_u32 s9, s68, 0
	v_add_f32_e32 v73, 1.0, v1
	v_add_f32_e32 v2, -1.0, v73
	v_sub_f32_e32 v3, v2, v73
	v_add_f32_e32 v3, 1.0, v3
	v_sub_f32_e32 v2, v1, v2
	v_add_f32_e32 v76, v2, v3
	v_frexp_mant_f32_e32 v2, v73
	v_cmp_gt_f32_e32 vcc, s39, v2
	v_cvt_f64_f32_e32 v[2:3], v73
	v_frexp_exp_i32_f64_e32 v2, v[2:3]
	v_subbrev_co_u32_e32 v2, vcc, 0, v2, vcc
	v_sub_u32_e32 v3, 0, v2
	v_ldexp_f32 v73, v73, v3
	v_ldexp_f32 v3, v76, v3
	v_add_f32_e32 v76, -1.0, v73
	v_add_f32_e32 v77, 1.0, v76
	v_sub_f32_e32 v77, v73, v77
	v_add_f32_e32 v77, v3, v77
	v_add_f32_e32 v78, v76, v77
	v_sub_f32_e32 v76, v78, v76
	v_sub_f32_e32 v76, v77, v76
	v_add_f32_e32 v77, 1.0, v73
	v_add_f32_e32 v79, -1.0, v77
	v_sub_f32_e32 v73, v73, v79
	v_add_f32_e32 v3, v3, v73
	v_add_f32_e32 v73, v77, v3
	v_sub_f32_e32 v77, v73, v77
	v_sub_f32_e32 v3, v3, v77
	v_rcp_f32_e32 v77, v73
	v_cvt_f32_i32_e32 v2, v2
	v_cmp_neq_f32_e32 vcc, s40, v1
	v_and_b32_e32 v71, 63, v84
	v_mul_f32_e32 v79, v78, v77
	v_mul_f32_e32 v80, v73, v79
	v_fma_f32 v81, v79, v73, -v80
	v_fmac_f32_e32 v81, v79, v3
	v_add_f32_e32 v82, v80, v81
	v_sub_f32_e32 v83, v78, v82
	v_sub_f32_e32 v78, v78, v83
	v_sub_f32_e32 v80, v82, v80
	v_sub_f32_e32 v78, v78, v82
	v_add_f32_e32 v76, v76, v78
	v_sub_f32_e32 v78, v80, v81
	v_add_f32_e32 v76, v78, v76
	v_add_f32_e32 v78, v83, v76
	v_mul_f32_e32 v80, v77, v78
	v_mul_f32_e32 v81, v73, v80
	v_fma_f32 v73, v80, v73, -v81
	v_fmac_f32_e32 v73, v80, v3
	v_sub_f32_e32 v3, v83, v78
	v_add_f32_e32 v3, v76, v3
	v_add_f32_e32 v76, v81, v73
	v_sub_f32_e32 v82, v78, v76
	v_sub_f32_e32 v78, v78, v82
	v_sub_f32_e32 v81, v76, v81
	v_sub_f32_e32 v76, v78, v76
	v_add_f32_e32 v3, v3, v76
	v_sub_f32_e32 v73, v81, v73
	v_add_f32_e32 v3, v73, v3
	v_add_f32_e32 v73, v79, v80
	v_add_f32_e32 v3, v82, v3
	v_sub_f32_e32 v76, v73, v79
	v_mul_f32_e32 v3, v77, v3
	v_sub_f32_e32 v76, v80, v76
	v_add_f32_e32 v3, v76, v3
	v_mul_f32_e32 v79, 0x3f317218, v2
	v_add_f32_e32 v76, v73, v3
	v_fma_f32 v80, v2, s62, -v79
	v_mul_f32_e32 v77, v76, v76
	v_fmac_f32_e32 v80, 0xb102e308, v2
	v_sub_f32_e32 v2, v76, v73
	v_fmamk_f32 v78, v77, 0x3e9b6dac, v236
	v_sub_f32_e32 v2, v3, v2
	v_add_f32_e32 v3, v79, v80
	v_fmaak_f32 v78, v77, v78, 0x3f2aaada
	v_sub_f32_e32 v73, v3, v79
	v_ldexp_f32 v79, v76, 1
	v_mul_f32_e32 v76, v76, v77
	v_mul_f32_e32 v76, v76, v78
	v_add_f32_e32 v77, v79, v76
	v_sub_f32_e32 v78, v77, v79
	v_ldexp_f32 v2, v2, 1
	v_sub_f32_e32 v76, v76, v78
	v_add_f32_e32 v2, v2, v76
	v_add_f32_e32 v76, v77, v2
	v_sub_f32_e32 v77, v76, v77
	v_sub_f32_e32 v2, v2, v77
	v_add_f32_e32 v77, v3, v76
	v_sub_f32_e32 v78, v77, v3
	v_sub_f32_e32 v79, v77, v78
	v_sub_f32_e32 v73, v80, v73
	v_sub_f32_e32 v3, v3, v79
	v_sub_f32_e32 v76, v76, v78
	v_add_f32_e32 v3, v76, v3
	v_add_f32_e32 v76, v73, v2
	v_sub_f32_e32 v78, v76, v73
	v_sub_f32_e32 v79, v76, v78
	v_sub_f32_e32 v73, v73, v79
	v_sub_f32_e32 v2, v2, v78
	v_add_f32_e32 v3, v76, v3
	v_add_f32_e32 v2, v2, v73
	v_add_f32_e32 v73, v77, v3
	v_sub_f32_e32 v76, v73, v77
	v_sub_f32_e32 v3, v3, v76
	v_add_f32_e32 v2, v2, v3
	v_add_f32_e32 v2, v73, v2
	v_cndmask_b32_e32 v2, v219, v2, vcc
	v_cmp_ngt_f32_e32 vcc, -1.0, v1
	s_add_u32 s8, s8, s10
	s_addc_u32 s9, s9, 0
	v_cndmask_b32_e32 v2, v220, v2, vcc
	v_cmp_neq_f32_e32 vcc, -1.0, v1
	v_lshlrev_b32_e32 v76, 1, v71
	v_mov_b32_e32 v77, v0
	v_cndmask_b32_e32 v2, v221, v2, vcc
	v_cmp_lt_f32_e64 vcc, |v1|, s28
	v_lshl_add_u64 v[90:91], s[8:9], 0, v[76:77]
	s_movk_i32 s8, 0x90
	v_cndmask_b32_e32 v1, v2, v1, vcc
	v_lshlrev_b32_e32 v2, 3, v85
	v_ashrrev_i32_e32 v3, 31, v2
	v_lshlrev_b64 v[76:77], 11, v[2:3]
	v_lshl_add_u64 v[76:77], v[90:91], 0, v[76:77]
	global_load_ushort v3, v[76:77], off
	v_or_b32_e32 v76, 1, v2
	v_ashrrev_i32_e32 v77, 31, v76
	v_lshlrev_b64 v[76:77], 11, v[76:77]
	v_lshl_add_u64 v[76:77], v[90:91], 0, v[76:77]
	global_load_ushort v87, v[76:77], off
	v_or_b32_e32 v76, 2, v2
	v_ashrrev_i32_e32 v77, 31, v76
	v_lshlrev_b64 v[76:77], 11, v[76:77]
	v_lshl_add_u64 v[76:77], v[90:91], 0, v[76:77]
	global_load_ushort v126, v[76:77], off
	v_or_b32_e32 v76, 3, v2
	v_ashrrev_i32_e32 v77, 31, v76
	v_lshlrev_b64 v[76:77], 11, v[76:77]
	v_lshl_add_u64 v[76:77], v[90:91], 0, v[76:77]
	global_load_ushort v127, v[76:77], off
	v_or_b32_e32 v76, 4, v2
	v_ashrrev_i32_e32 v77, 31, v76
	v_lshlrev_b64 v[76:77], 11, v[76:77]
	v_lshl_add_u64 v[76:77], v[90:91], 0, v[76:77]
	global_load_ushort v128, v[76:77], off
	v_or_b32_e32 v76, 5, v2
	v_ashrrev_i32_e32 v77, 31, v76
	v_lshlrev_b64 v[76:77], 11, v[76:77]
	v_lshl_add_u64 v[76:77], v[90:91], 0, v[76:77]
	global_load_ushort v129, v[76:77], off
	v_or_b32_e32 v76, 6, v2
	v_ashrrev_i32_e32 v77, 31, v76
	v_lshlrev_b64 v[76:77], 11, v[76:77]
	v_lshl_add_u64 v[76:77], v[90:91], 0, v[76:77]
	global_load_ushort v130, v[76:77], off
	v_or_b32_e32 v76, 7, v2
	v_ashrrev_i32_e32 v77, 31, v76
	v_lshlrev_b64 v[76:77], 11, v[76:77]
	v_lshl_add_u64 v[76:77], v[90:91], 0, v[76:77]
	global_load_ushort v131, v[76:77], off
	v_mov_b32_e32 v77, 0x6400
	v_cndmask_b32_e64 v77, v217, v77, s[6:7]
	v_lshlrev_b32_e32 v71, 2, v71
	v_mul_lo_u32 v73, v86, s8
	v_add_u32_e32 v77, 0, v77
	v_and_b32_e32 v78, 48, v84
	v_lshl_add_u32 v69, v69, 2, 0
	v_add_u32_e32 v73, 0, v73
	v_lshlrev_b32_e32 v76, 8, v86
	v_add_u32_e32 v78, 0, v78
	v_lshlrev_b32_e32 v75, 10, v75
	v_add3_u32 v68, v77, v70, v68
	v_mul_u32_u24_e32 v70, 0x90, v74
	v_lshl_or_b32 v74, v85, 11, v71
	v_readlane_b32 s12, v255, 6
	s_mov_b32 s52, 0
	v_mul_f32_e32 v1, 0xc1000000, v1
	v_add_u32_e32 v132, 0, v71
	v_add_u32_e32 v133, 61, v86
	v_add_u32_e32 v134, 64, v2
	v_cmp_lt_i32_e64 s[8:9], 0, v85
	v_cmp_eq_u32_e64 s[10:11], 7, v85
	v_add_u32_e32 v135, 0, v74
	v_add_u32_e32 v136, s12, v71
	v_add_u32_e32 v137, v73, v72
	v_add_u32_e32 v138, v69, v76
	v_add_u32_e32 v139, v78, v70
	v_add_u32_e32 v140, v68, v75
	s_waitcnt vmcnt(0)
	s_branch .LBB0_275

.LBB0_277:
	v_add_u32_e32 v109, s65, v86
	v_cmp_lt_i32_e32 vcc, 2, v109
	v_mov_b32_e32 v92, 0
	v_mov_b32_e32 v94, 0
	v_mov_b32_e32 v95, 0
	v_mov_b32_e32 v96, 0
	v_mov_b32_e32 v97, 0
	v_mov_b32_e32 v98, 0
	v_mov_b32_e32 v99, 0
	v_mov_b32_e32 v100, 0
	v_mov_b32_e32 v101, 0
	s_and_saveexec_b64 s[16:17], vcc
	s_cbranch_execz .LBB0_279
	s_nop 0
	v_lshlrev_b32_e32 v94, 16, v52
	v_and_b32_e32 v95, 0xffff0000, v52
	v_lshlrev_b32_e32 v96, 16, v53
	v_and_b32_e32 v97, 0xffff0000, v53
	v_lshlrev_b32_e32 v98, 16, v54
	v_and_b32_e32 v99, 0xffff0000, v54
	v_lshlrev_b32_e32 v100, 16, v55
	v_and_b32_e32 v101, 0xffff0000, v55
.LBB0_279:
	s_or_b64 exec, exec, s[16:17]
	v_cmp_lt_i32_e32 vcc, 1, v109
	v_mov_b32_e32 v93, 0
	v_mov_b32_e32 v102, 0
	v_mov_b32_e32 v103, 0
	v_mov_b32_e32 v104, 0
	v_mov_b32_e32 v105, 0
	v_mov_b32_e32 v106, 0
	v_mov_b32_e32 v107, 0
	s_and_saveexec_b64 s[16:17], vcc
	s_cbranch_execz .LBB0_281
	s_nop 0
	v_lshlrev_b32_e32 v92, 16, v56
	v_and_b32_e32 v93, 0xffff0000, v56
	v_lshlrev_b32_e32 v102, 16, v57
	v_and_b32_e32 v103, 0xffff0000, v57
	v_lshlrev_b32_e32 v104, 16, v58
	v_and_b32_e32 v105, 0xffff0000, v58
	v_lshlrev_b32_e32 v106, 16, v59
	v_and_b32_e32 v107, 0xffff0000, v59
.LBB0_281:
	s_or_b64 exec, exec, s[16:17]
	v_cmp_lt_i32_e32 vcc, 0, v109
	v_mov_b32_e32 v108, 0
	v_mov_b32_e32 v110, 0
	v_mov_b32_e32 v111, 0
	v_mov_b32_e32 v112, 0
	v_mov_b32_e32 v113, 0
	v_mov_b32_e32 v114, 0
	v_mov_b32_e32 v115, 0
	v_mov_b32_e32 v116, 0
	v_mov_b32_e32 v117, 0
	s_and_saveexec_b64 s[16:17], vcc
	s_cbranch_execz .LBB0_283
	s_nop 0
	v_lshlrev_b32_e32 v110, 16, v60
	v_and_b32_e32 v111, 0xffff0000, v60
	v_lshlrev_b32_e32 v112, 16, v61
	v_and_b32_e32 v113, 0xffff0000, v61
	v_lshlrev_b32_e32 v114, 16, v62
	v_and_b32_e32 v115, 0xffff0000, v62
	v_lshlrev_b32_e32 v116, 16, v63
	v_and_b32_e32 v117, 0xffff0000, v63
.LBB0_283:
	s_or_b64 exec, exec, s[16:17]
	v_cmp_lt_i32_e32 vcc, -1, v109
	v_mov_b32_e32 v109, 0
	v_mov_b32_e32 v122, 0
	v_mov_b32_e32 v123, 0
	v_mov_b32_e32 v120, 0
	v_mov_b32_e32 v121, 0
	v_mov_b32_e32 v118, 0
	v_mov_b32_e32 v119, 0
	s_and_saveexec_b64 s[16:17], vcc
	s_cbranch_execz .LBB0_285
	s_nop 0
	v_lshlrev_b32_e32 v108, 16, v64
	v_and_b32_e32 v109, 0xffff0000, v64
	v_lshlrev_b32_e32 v122, 16, v65
	v_and_b32_e32 v123, 0xffff0000, v65
	v_lshlrev_b32_e32 v120, 16, v66
	v_and_b32_e32 v121, 0xffff0000, v66
	v_lshlrev_b32_e32 v118, 16, v67
	v_and_b32_e32 v119, 0xffff0000, v67
.LBB0_285:
	s_or_b64 exec, exec, s[16:17]
	s_nop 0
	v_pk_fma_f32 v[94:95], v[24:25], v[94:95], v[16:17]
	v_pk_fma_f32 v[96:97], v[26:27], v[96:97], v[18:19]
	v_pk_fma_f32 v[98:99], v[20:21], v[98:99], v[12:13]
	v_pk_fma_f32 v[100:101], v[22:23], v[100:101], v[14:15]
	s_nop 0
	v_pk_fma_f32 v[92:93], v[28:29], v[92:93], v[94:95]
	v_pk_fma_f32 v[94:95], v[30:31], v[102:103], v[96:97]
	s_nop 0
	v_pk_fma_f32 v[96:97], v[32:33], v[104:105], v[98:99]
	v_pk_fma_f32 v[98:99], v[34:35], v[106:107], v[100:101]
	s_nop 0
	v_pk_fma_f32 v[92:93], v[36:37], v[110:111], v[92:93]
	v_pk_fma_f32 v[94:95], v[38:39], v[112:113], v[94:95]
	s_nop 0
	v_pk_fma_f32 v[100:101], v[40:41], v[114:115], v[96:97]
	v_pk_fma_f32 v[102:103], v[42:43], v[116:117], v[98:99]
	s_nop 0
	v_pk_fma_f32 v[92:93], v[44:45], v[108:109], v[92:93]
	v_pk_fma_f32 v[94:95], v[46:47], v[122:123], v[94:95]
	v_cvt_pk_bf16_f32 v96, v92, v93
	s_nop 0
	v_pk_fma_f32 v[100:101], v[48:49], v[120:121], v[100:101]
	v_cvt_pk_bf16_f32 v97, v94, v95
	v_pk_fma_f32 v[102:103], v[50:51], v[118:119], v[102:103]
	v_cvt_pk_bf16_f32 v98, v100, v101
	s_nop 0
	v_cvt_pk_bf16_f32 v99, v102, v103
	ds_write_b128 v137, v[96:99]
	ds_write_b128 v138, v[92:95] offset:9216
	ds_write_b128 v138, v[100:103] offset:9232
	s_waitcnt lgkmcnt(0)
	s_barrier
	ds_read_b128 v[92:95], v139
	ds_read_b128 v[96:99], v139 offset:64
	s_waitcnt lgkmcnt(1)
	v_mfma_f32_16x16x32_bf16 v[92:95], v[92:95], v[4:7], 0
	s_waitcnt lgkmcnt(0)
	v_mfma_f32_16x16x32_bf16 v[92:95], v[96:99], v[8:11], v[92:95]
	s_nop 7
	v_add_f32_e32 v92, v124, v92
	v_mul_f32_e32 v92, 0xbfb8aa3b, v92
	v_exp_f32_e32 v92, v92
	v_add_f32_e32 v93, v124, v93
	v_mul_f32_e32 v93, 0xbfb8aa3b, v93
	v_exp_f32_e32 v93, v93
	v_add_f32_e32 v92, 1.0, v92
	v_div_scale_f32 v96, s[16:17], v92, v92, 1.0
	v_rcp_f32_e32 v97, v96
	v_add_f32_e32 v93, 1.0, v93
	v_add_f32_e32 v94, v124, v94
	v_mul_f32_e32 v94, 0xbfb8aa3b, v94
	v_fma_f32 v98, -v96, v97, 1.0
	v_fmac_f32_e32 v97, v98, v97
	v_div_scale_f32 v98, vcc, 1.0, v92, 1.0
	v_mul_f32_e32 v99, v98, v97
	v_fma_f32 v100, -v96, v99, v98
	v_fmac_f32_e32 v99, v100, v97
	v_fma_f32 v96, -v96, v99, v98
	v_div_fmas_f32 v96, v96, v97, v99
	v_div_scale_f32 v97, s[16:17], v93, v93, 1.0
	v_rcp_f32_e32 v98, v97
	v_div_fixup_f32 v92, v96, v92, 1.0
	v_mul_f32_e32 v96, v1, v92
	v_cndmask_b32_e64 v92, v92, v96, s[6:7]
	v_fma_f32 v96, -v97, v98, 1.0
	v_fmac_f32_e32 v98, v96, v98
	v_div_scale_f32 v96, vcc, 1.0, v93, 1.0
	v_mul_f32_e32 v99, v96, v98
	v_exp_f32_e32 v94, v94
	v_fma_f32 v100, -v97, v99, v96
	v_fmac_f32_e32 v99, v100, v98
	v_fma_f32 v96, -v97, v99, v96
	v_div_fmas_f32 v96, v96, v98, v99
	v_add_f32_e32 v94, 1.0, v94
	v_div_fixup_f32 v93, v96, v93, 1.0
	v_div_scale_f32 v96, s[16:17], v94, v94, 1.0
	v_rcp_f32_e32 v97, v96
	v_mul_f32_e32 v98, v1, v93
	v_cndmask_b32_e64 v93, v93, v98, s[6:7]
	ds_write2st64_b32 v140, v92, v93 offset1:1
	v_fma_f32 v92, -v96, v97, 1.0
	v_add_f32_e32 v95, v124, v95
	v_fmac_f32_e32 v97, v92, v97
	v_div_scale_f32 v92, vcc, 1.0, v94, 1.0
	v_mul_f32_e32 v95, 0xbfb8aa3b, v95
	v_mul_f32_e32 v93, v92, v97
	v_exp_f32_e32 v95, v95
	v_fma_f32 v98, -v96, v93, v92
	v_fmac_f32_e32 v93, v98, v97
	v_fma_f32 v92, -v96, v93, v92
	v_div_fmas_f32 v92, v92, v97, v93
	v_add_f32_e32 v93, 1.0, v95
	v_div_scale_f32 v95, s[16:17], v93, v93, 1.0
	v_rcp_f32_e32 v96, v95
	v_div_fixup_f32 v92, v92, v94, 1.0
	v_mul_f32_e32 v94, v1, v92
	v_cndmask_b32_e64 v92, v92, v94, s[6:7]
	v_fma_f32 v94, -v95, v96, 1.0
	v_fmac_f32_e32 v96, v94, v96
	v_div_scale_f32 v94, vcc, 1.0, v93, 1.0
	v_mul_f32_e32 v97, v94, v96
	v_fma_f32 v98, -v95, v97, v94
	v_fmac_f32_e32 v97, v98, v96
	v_fma_f32 v94, -v95, v97, v94
	v_div_fmas_f32 v94, v94, v96, v97
	v_div_fixup_f32 v93, v94, v93, 1.0
	v_mul_f32_e32 v94, v1, v93
	v_cndmask_b32_e64 v93, v93, v94, s[6:7]
	ds_write2st64_b32 v140, v92, v93 offset0:2 offset1:3
	ds_read_b128 v[92:95], v139 offset:2304
	ds_read_b128 v[96:99], v139 offset:2368
	s_waitcnt lgkmcnt(1)
	v_mfma_f32_16x16x32_bf16 v[92:95], v[92:95], v[4:7], 0
	s_waitcnt lgkmcnt(0)
	v_mfma_f32_16x16x32_bf16 v[92:95], v[96:99], v[8:11], v[92:95]
	s_nop 7
	v_add_f32_e32 v92, v124, v92
	v_mul_f32_e32 v92, 0xbfb8aa3b, v92
	v_exp_f32_e32 v92, v92
	v_add_f32_e32 v93, v124, v93
	v_mul_f32_e32 v93, 0xbfb8aa3b, v93
	v_exp_f32_e32 v93, v93
	v_add_f32_e32 v92, 1.0, v92
	v_div_scale_f32 v96, s[16:17], v92, v92, 1.0
	v_rcp_f32_e32 v97, v96
	v_add_f32_e32 v93, 1.0, v93
	v_add_f32_e32 v94, v124, v94
	v_mul_f32_e32 v94, 0xbfb8aa3b, v94
	v_fma_f32 v98, -v96, v97, 1.0
	v_fmac_f32_e32 v97, v98, v97
	v_div_scale_f32 v98, vcc, 1.0, v92, 1.0
	v_mul_f32_e32 v99, v98, v97
	v_fma_f32 v100, -v96, v99, v98
	v_fmac_f32_e32 v99, v100, v97
	v_fma_f32 v96, -v96, v99, v98
	v_div_fmas_f32 v96, v96, v97, v99
	v_div_scale_f32 v97, s[16:17], v93, v93, 1.0
	v_rcp_f32_e32 v98, v97
	v_div_fixup_f32 v92, v96, v92, 1.0
	v_mul_f32_e32 v96, v1, v92
	v_cndmask_b32_e64 v92, v92, v96, s[6:7]
	v_fma_f32 v96, -v97, v98, 1.0
	v_fmac_f32_e32 v98, v96, v98
	v_div_scale_f32 v96, vcc, 1.0, v93, 1.0
	v_mul_f32_e32 v99, v96, v98
	v_exp_f32_e32 v94, v94
	v_fma_f32 v100, -v97, v99, v96
	v_fmac_f32_e32 v99, v100, v98
	v_fma_f32 v96, -v97, v99, v96
	v_div_fmas_f32 v96, v96, v98, v99
	v_add_f32_e32 v94, 1.0, v94
	v_div_fixup_f32 v93, v96, v93, 1.0
	v_div_scale_f32 v96, s[16:17], v94, v94, 1.0
	v_rcp_f32_e32 v97, v96
	v_mul_f32_e32 v98, v1, v93
	v_cndmask_b32_e64 v93, v93, v98, s[6:7]
	ds_write2st64_b32 v140, v92, v93 offset0:16 offset1:17
	v_fma_f32 v92, -v96, v97, 1.0
	v_add_f32_e32 v95, v124, v95
	v_fmac_f32_e32 v97, v92, v97
	v_div_scale_f32 v92, vcc, 1.0, v94, 1.0
	v_mul_f32_e32 v95, 0xbfb8aa3b, v95
	v_mul_f32_e32 v93, v92, v97
	v_exp_f32_e32 v95, v95
	v_fma_f32 v98, -v96, v93, v92
	v_fmac_f32_e32 v93, v98, v97
	v_fma_f32 v92, -v96, v93, v92
	v_div_fmas_f32 v92, v92, v97, v93
	v_add_f32_e32 v93, 1.0, v95
	v_div_scale_f32 v95, s[16:17], v93, v93, 1.0
	v_rcp_f32_e32 v96, v95
	v_div_fixup_f32 v92, v92, v94, 1.0
	v_mul_f32_e32 v94, v1, v92
	v_cndmask_b32_e64 v92, v92, v94, s[6:7]
	v_fma_f32 v94, -v95, v96, 1.0
	v_fmac_f32_e32 v96, v94, v96
	v_div_scale_f32 v94, vcc, 1.0, v93, 1.0
	v_mul_f32_e32 v97, v94, v96
	v_fma_f32 v98, -v95, v97, v94
	v_fmac_f32_e32 v97, v98, v96
	v_fma_f32 v94, -v95, v97, v94
	v_div_fmas_f32 v94, v94, v96, v97
	v_div_fixup_f32 v93, v94, v93, 1.0
	v_mul_f32_e32 v94, v1, v93
	v_cndmask_b32_e64 v93, v93, v94, s[6:7]
	ds_write2st64_b32 v140, v92, v93 offset0:18 offset1:19
	ds_read_b128 v[92:95], v139 offset:4608
	ds_read_b128 v[96:99], v139 offset:4672
	s_waitcnt lgkmcnt(1)
	v_mfma_f32_16x16x32_bf16 v[92:95], v[92:95], v[4:7], 0
	s_waitcnt lgkmcnt(0)
	v_mfma_f32_16x16x32_bf16 v[92:95], v[96:99], v[8:11], v[92:95]
	s_nop 7
	v_add_f32_e32 v92, v124, v92
	v_mul_f32_e32 v92, 0xbfb8aa3b, v92
	v_exp_f32_e32 v92, v92
	v_add_f32_e32 v93, v124, v93
	v_mul_f32_e32 v93, 0xbfb8aa3b, v93
	v_exp_f32_e32 v93, v93
	v_add_f32_e32 v92, 1.0, v92
	v_div_scale_f32 v96, s[16:17], v92, v92, 1.0
	v_rcp_f32_e32 v97, v96
	v_add_f32_e32 v93, 1.0, v93
	v_add_f32_e32 v94, v124, v94
	v_mul_f32_e32 v94, 0xbfb8aa3b, v94
	v_fma_f32 v98, -v96, v97, 1.0
	v_fmac_f32_e32 v97, v98, v97
	v_div_scale_f32 v98, vcc, 1.0, v92, 1.0
	v_mul_f32_e32 v99, v98, v97
	v_fma_f32 v100, -v96, v99, v98
	v_fmac_f32_e32 v99, v100, v97
	v_fma_f32 v96, -v96, v99, v98
	v_div_fmas_f32 v96, v96, v97, v99
	v_div_scale_f32 v97, s[16:17], v93, v93, 1.0
	v_rcp_f32_e32 v98, v97
	v_div_fixup_f32 v92, v96, v92, 1.0
	v_mul_f32_e32 v96, v1, v92
	v_cndmask_b32_e64 v92, v92, v96, s[6:7]
	v_fma_f32 v96, -v97, v98, 1.0
	v_fmac_f32_e32 v98, v96, v98
	v_div_scale_f32 v96, vcc, 1.0, v93, 1.0
	v_mul_f32_e32 v99, v96, v98
	v_exp_f32_e32 v94, v94
	v_fma_f32 v100, -v97, v99, v96
	v_fmac_f32_e32 v99, v100, v98
	v_fma_f32 v96, -v97, v99, v96
	v_div_fmas_f32 v96, v96, v98, v99
	v_add_f32_e32 v94, 1.0, v94
	v_div_fixup_f32 v93, v96, v93, 1.0
	v_div_scale_f32 v96, s[16:17], v94, v94, 1.0
	v_rcp_f32_e32 v97, v96
	v_mul_f32_e32 v98, v1, v93
	v_cndmask_b32_e64 v93, v93, v98, s[6:7]
	ds_write2st64_b32 v140, v92, v93 offset0:32 offset1:33
	v_fma_f32 v92, -v96, v97, 1.0
	v_add_f32_e32 v95, v124, v95
	v_fmac_f32_e32 v97, v92, v97
	v_div_scale_f32 v92, vcc, 1.0, v94, 1.0
	v_mul_f32_e32 v95, 0xbfb8aa3b, v95
	v_mul_f32_e32 v93, v92, v97
	v_exp_f32_e32 v95, v95
	v_fma_f32 v98, -v96, v93, v92
	v_fmac_f32_e32 v93, v98, v97
	v_fma_f32 v92, -v96, v93, v92
	v_div_fmas_f32 v92, v92, v97, v93
	v_add_f32_e32 v93, 1.0, v95
	v_div_scale_f32 v95, s[16:17], v93, v93, 1.0
	v_rcp_f32_e32 v96, v95
	v_div_fixup_f32 v92, v92, v94, 1.0
	v_mul_f32_e32 v94, v1, v92
	v_cndmask_b32_e64 v92, v92, v94, s[6:7]
	v_fma_f32 v94, -v95, v96, 1.0
	v_fmac_f32_e32 v96, v94, v96
	v_div_scale_f32 v94, vcc, 1.0, v93, 1.0
	v_mul_f32_e32 v97, v94, v96
	v_fma_f32 v98, -v95, v97, v94
	v_fmac_f32_e32 v97, v98, v96
	v_fma_f32 v94, -v95, v97, v94
	v_div_fmas_f32 v94, v94, v96, v97
	v_div_fixup_f32 v93, v94, v93, 1.0
	v_mul_f32_e32 v94, v1, v93
	v_cndmask_b32_e64 v93, v93, v94, s[6:7]
	ds_write2st64_b32 v140, v92, v93 offset0:34 offset1:35
	ds_read_b128 v[92:95], v139 offset:6912
	ds_read_b128 v[96:99], v139 offset:6976
	s_waitcnt lgkmcnt(1)
	v_mfma_f32_16x16x32_bf16 v[92:95], v[92:95], v[4:7], 0
	s_waitcnt lgkmcnt(0)
	v_mfma_f32_16x16x32_bf16 v[92:95], v[96:99], v[8:11], v[92:95]
	s_nop 7
	v_add_f32_e32 v92, v124, v92
	v_mul_f32_e32 v92, 0xbfb8aa3b, v92
	v_exp_f32_e32 v92, v92
	v_add_f32_e32 v93, v124, v93
	v_mul_f32_e32 v93, 0xbfb8aa3b, v93
	v_exp_f32_e32 v93, v93
	v_add_f32_e32 v92, 1.0, v92
	v_div_scale_f32 v96, s[16:17], v92, v92, 1.0
	v_rcp_f32_e32 v97, v96
	v_add_f32_e32 v93, 1.0, v93
	v_add_f32_e32 v94, v124, v94
	v_mul_f32_e32 v94, 0xbfb8aa3b, v94
	v_fma_f32 v98, -v96, v97, 1.0
	v_fmac_f32_e32 v97, v98, v97
	v_div_scale_f32 v98, vcc, 1.0, v92, 1.0
	v_mul_f32_e32 v99, v98, v97
	v_fma_f32 v100, -v96, v99, v98
	v_fmac_f32_e32 v99, v100, v97
	v_fma_f32 v96, -v96, v99, v98
	v_div_fmas_f32 v96, v96, v97, v99
	v_div_scale_f32 v97, s[16:17], v93, v93, 1.0
	v_rcp_f32_e32 v98, v97
	v_div_fixup_f32 v92, v96, v92, 1.0
	v_mul_f32_e32 v96, v1, v92
	v_cndmask_b32_e64 v92, v92, v96, s[6:7]
	v_fma_f32 v96, -v97, v98, 1.0
	v_fmac_f32_e32 v98, v96, v98
	v_div_scale_f32 v96, vcc, 1.0, v93, 1.0
	v_mul_f32_e32 v99, v96, v98
	v_exp_f32_e32 v94, v94
	v_fma_f32 v100, -v97, v99, v96
	v_fmac_f32_e32 v99, v100, v98
	v_fma_f32 v96, -v97, v99, v96
	v_div_fmas_f32 v96, v96, v98, v99
	v_add_f32_e32 v94, 1.0, v94
	v_div_fixup_f32 v93, v96, v93, 1.0
	v_div_scale_f32 v96, s[16:17], v94, v94, 1.0
	v_rcp_f32_e32 v97, v96
	v_mul_f32_e32 v98, v1, v93
	v_cndmask_b32_e64 v93, v93, v98, s[6:7]
	ds_write2st64_b32 v140, v92, v93 offset0:48 offset1:49
	v_fma_f32 v92, -v96, v97, 1.0
	v_add_f32_e32 v95, v124, v95
	v_fmac_f32_e32 v97, v92, v97
	v_div_scale_f32 v92, vcc, 1.0, v94, 1.0
	v_mul_f32_e32 v95, 0xbfb8aa3b, v95
	v_mul_f32_e32 v93, v92, v97
	v_exp_f32_e32 v95, v95
	v_fma_f32 v98, -v96, v93, v92
	v_fmac_f32_e32 v93, v98, v97
	v_fma_f32 v92, -v96, v93, v92
	v_div_fmas_f32 v92, v92, v97, v93
	v_add_f32_e32 v93, 1.0, v95
	v_div_scale_f32 v95, s[16:17], v93, v93, 1.0
	v_rcp_f32_e32 v96, v95
	v_div_fixup_f32 v92, v92, v94, 1.0
	v_mul_f32_e32 v94, v1, v92
	v_cndmask_b32_e64 v92, v92, v94, s[6:7]
	v_fma_f32 v94, -v95, v96, 1.0
	v_fmac_f32_e32 v96, v94, v96
	v_div_scale_f32 v94, vcc, 1.0, v93, 1.0
	v_mul_f32_e32 v97, v94, v96
	v_fma_f32 v98, -v95, v97, v94
	v_fmac_f32_e32 v97, v98, v96
	v_fma_f32 v94, -v95, v97, v94
	v_div_fmas_f32 v94, v94, v96, v97
	v_div_fixup_f32 v93, v94, v93, 1.0
	v_mul_f32_e32 v94, v1, v93
	v_cndmask_b32_e64 v93, v93, v94, s[6:7]
	ds_write2st64_b32 v140, v92, v93 offset0:50 offset1:51
	s_waitcnt lgkmcnt(0)
	s_barrier
	ds_read2st64_b32 v[94:95], v135 offset0:100 offset1:101
	ds_read2st64_b32 v[96:97], v135 offset0:102 offset1:103
	ds_read2st64_b32 v[104:105], v135 offset0:104 offset1:105
	ds_read2st64_b32 v[106:107], v135 offset0:106 offset1:107
	s_and_b32 s16, s65, 64
	s_waitcnt lgkmcnt(3)
	v_add_f32_e32 v93, v94, v94
	v_mul_f32_e32 v92, 0x3fb8aa3b, v94
	v_fmamk_f32 v94, v93, 0x39500d01, v210
	v_fmaak_f32 v94, v93, v94, 0x3c088889
	v_exp_f32_e32 v92, v92
	v_fmaak_f32 v94, v93, v94, 0x3d2aaaab
	v_fmaak_f32 v94, v93, v94, 0x3e2aaaab
	v_fma_f32 v94, v93, v94, 0.5
	v_fma_f32 v94, v93, v94, 1.0
	v_mul_f32_e64 v94, v94, -v93
	v_fma_f32 v98, -v92, v92, 1.0
	v_cmp_lt_f32_e32 vcc, s29, v93
	s_nop 1
	v_cndmask_b32_e32 v93, v98, v94, vcc
	ds_read2st64_b32 v[98:99], v135 offset0:36 offset1:37
	ds_read2st64_b32 v[100:101], v135 offset0:164 offset1:165
	ds_read2st64_b32 v[102:103], v135 offset0:166 offset1:167
	ds_read2st64_b32 v[108:109], v135 offset0:168 offset1:169
	ds_read2st64_b32 v[110:111], v135 offset0:170 offset1:171
	ds_read2st64_b32 v[112:113], v135 offset0:38 offset1:39
	ds_read2st64_b32 v[114:115], v135 offset0:40 offset1:41
	ds_read2st64_b32 v[116:117], v135 offset0:42 offset1:43
	s_waitcnt lgkmcnt(6)
	v_mul_f32_e32 v94, v100, v98
	v_mul_f32_e32 v98, 0x3fb8aa3b, v95
	v_add_f32_e32 v95, v95, v95
	v_fmamk_f32 v100, v95, 0x39500d01, v210
	v_fmaak_f32 v100, v95, v100, 0x3c088889
	v_exp_f32_e32 v98, v98
	v_fmaak_f32 v100, v95, v100, 0x3d2aaaab
	v_fmaak_f32 v100, v95, v100, 0x3e2aaaab
	v_sqrt_f32_e32 v93, v93
	v_fma_f32 v100, v95, v100, 0.5
	v_fma_f32 v100, v95, v100, 1.0
	v_mul_f32_e64 v100, v100, -v95
	v_fma_f32 v118, -v98, v98, 1.0
	v_cmp_lt_f32_e32 vcc, s29, v95
	s_nop 1
	v_cndmask_b32_e32 v95, v118, v100, vcc
	v_sqrt_f32_e32 v100, v95
	v_mul_f32_e32 v95, v94, v93
	v_mul_f32_e32 v94, 0x3fb8aa3b, v96
	v_mul_f32_e32 v93, v101, v99
	v_exp_f32_e32 v99, v94
	v_add_f32_e32 v94, v96, v96
	v_fmamk_f32 v96, v94, 0x39500d01, v210
	v_fmaak_f32 v96, v94, v96, 0x3c088889
	v_fmaak_f32 v96, v94, v96, 0x3d2aaaab
	v_fmaak_f32 v96, v94, v96, 0x3e2aaaab
	v_fma_f32 v96, v94, v96, 0.5
	v_fma_f32 v96, v94, v96, 1.0
	v_mul_f32_e32 v93, v93, v100
	v_mul_f32_e64 v96, v96, -v94
	v_fma_f32 v100, -v99, v99, 1.0
	v_cmp_lt_f32_e32 vcc, s29, v94
	v_fmac_f32_e32 v95, 0, v92
	v_fmac_f32_e32 v93, v98, v95
	v_cndmask_b32_e32 v94, v100, v96, vcc
	v_sqrt_f32_e32 v94, v94
	s_waitcnt lgkmcnt(2)
	v_mul_f32_e32 v96, v102, v112
	v_mul_f32_e32 v98, v92, v98
	v_mul_f32_e32 v94, v96, v94
	v_mul_f32_e32 v96, 0x3fb8aa3b, v97
	v_exp_f32_e32 v100, v96
	v_add_f32_e32 v96, v97, v97
	v_fmamk_f32 v97, v96, 0x39500d01, v210
	v_fmaak_f32 v97, v96, v97, 0x3c088889
	v_fmaak_f32 v97, v96, v97, 0x3d2aaaab
	v_fmaak_f32 v97, v96, v97, 0x3e2aaaab
	v_fma_f32 v97, v96, v97, 0.5
	v_fma_f32 v97, v96, v97, 1.0
	v_mul_f32_e64 v97, v97, -v96
	v_fma_f32 v101, -v100, v100, 1.0
	v_cmp_lt_f32_e32 vcc, s29, v96
	v_fmac_f32_e32 v94, v99, v93
	s_nop 0
	v_cndmask_b32_e32 v96, v101, v97, vcc
	v_sqrt_f32_e32 v96, v96
	v_mul_f32_e32 v97, v103, v113
	v_mul_f32_e32 v101, v98, v99
	v_mul_f32_e32 v96, v97, v96
	v_mul_f32_e32 v97, 0x3fb8aa3b, v104
	v_exp_f32_e32 v99, v97
	v_add_f32_e32 v97, v104, v104
	v_fmamk_f32 v102, v97, 0x39500d01, v210
	v_fmaak_f32 v102, v97, v102, 0x3c088889
	v_fmaak_f32 v102, v97, v102, 0x3d2aaaab
	v_fmaak_f32 v102, v97, v102, 0x3e2aaaab
	v_fma_f32 v102, v97, v102, 0.5
	v_fma_f32 v102, v97, v102, 1.0
	v_mul_f32_e64 v102, v102, -v97
	v_fma_f32 v103, -v99, v99, 1.0
	v_cmp_lt_f32_e32 vcc, s29, v97
	v_fmac_f32_e32 v96, v100, v94
	s_nop 0
	v_cndmask_b32_e32 v97, v103, v102, vcc
	v_sqrt_f32_e32 v97, v97
	v_add_f32_e32 v102, v105, v105
	v_mul_f32_e32 v103, v101, v100
	s_waitcnt lgkmcnt(1)
	v_mul_f32_e32 v100, v108, v114
	v_fmamk_f32 v104, v102, 0x39500d01, v210
	v_mul_f32_e32 v97, v100, v97
	v_mul_f32_e32 v100, 0x3fb8aa3b, v105
	v_fmaak_f32 v104, v102, v104, 0x3c088889
	v_exp_f32_e32 v100, v100
	v_fmaak_f32 v104, v102, v104, 0x3d2aaaab
	v_fmaak_f32 v104, v102, v104, 0x3e2aaaab
	v_fma_f32 v104, v102, v104, 0.5
	v_fma_f32 v104, v102, v104, 1.0
	v_mul_f32_e64 v104, v104, -v102
	v_fma_f32 v105, -v100, v100, 1.0
	v_cmp_lt_f32_e32 vcc, s29, v102
	v_fmac_f32_e32 v97, v99, v96
	s_nop 0
	v_cndmask_b32_e32 v102, v105, v104, vcc
	v_sqrt_f32_e32 v102, v102
	v_mul_f32_e32 v104, v103, v99
	v_mul_f32_e32 v99, v109, v115
	v_mul_f32_e32 v99, v99, v102
	v_mul_f32_e32 v102, 0x3fb8aa3b, v106
	v_exp_f32_e32 v108, v102
	v_add_f32_e32 v102, v106, v106
	v_fmamk_f32 v105, v102, 0x39500d01, v210
	v_fmaak_f32 v105, v102, v105, 0x3c088889
	v_fmaak_f32 v105, v102, v105, 0x3d2aaaab
	v_fmaak_f32 v105, v102, v105, 0x3e2aaaab
	v_fma_f32 v105, v102, v105, 0.5
	v_fma_f32 v105, v102, v105, 1.0
	v_mul_f32_e64 v105, v105, -v102
	v_fma_f32 v106, -v108, v108, 1.0
	v_cmp_lt_f32_e32 vcc, s29, v102
	v_fmac_f32_e32 v99, v100, v97
	s_nop 0
	v_cndmask_b32_e32 v102, v106, v105, vcc
	v_sqrt_f32_e32 v102, v102
	v_mul_f32_e32 v105, v104, v100
	s_waitcnt lgkmcnt(0)
	v_mul_f32_e32 v100, v110, v116
	v_mul_f32_e32 v102, v100, v102
	v_mul_f32_e32 v100, 0x3fb8aa3b, v107
	v_exp_f32_e32 v106, v100
	v_add_f32_e32 v100, v107, v107
	v_fmamk_f32 v107, v100, 0x39500d01, v210
	v_fmaak_f32 v107, v100, v107, 0x3c088889
	v_fmaak_f32 v107, v100, v107, 0x3d2aaaab
	v_fmaak_f32 v107, v100, v107, 0x3e2aaaab
	v_fma_f32 v107, v100, v107, 0.5
	v_fma_f32 v107, v100, v107, 1.0
	v_mul_f32_e64 v107, v107, -v100
	v_fma_f32 v109, -v106, v106, 1.0
	v_cmp_lt_f32_e32 vcc, s29, v100
	v_fmac_f32_e32 v102, v108, v99
	s_nop 0
	v_cndmask_b32_e32 v100, v109, v107, vcc
	v_sqrt_f32_e32 v100, v100
	v_mul_f32_e32 v107, v105, v108
	v_mul_f32_e32 v108, v111, v117
	v_mul_f32_e32 v100, v108, v100
	v_fmac_f32_e32 v100, v106, v102
	v_mul_f32_e32 v106, v107, v106
	v_lshl_add_u32 v108, s16, 2, v132
	ds_write2st64_b32 v125, v106, v100 offset0:228 offset1:236
	s_waitcnt lgkmcnt(0)
	s_barrier
	ds_read_b32 v108, v108 offset:62464
	s_and_saveexec_b64 s[16:17], s[8:9]
	s_cbranch_execz .LBB0_289
	s_mov_b64 s[78:79], 0
	v_mov_b32_e32 v109, v136
	v_mov_b32_e32 v110, v85

.LBB0_599:
	s_and_b64 vcc, exec, s[76:77]
	s_cbranch_vccz .LBB0_606
	v_mov_b32_e32 v1, v208
	s_mov_b32 s6, s2
	s_waitcnt vmcnt(1)
	v_ashrrev_i32_e32 v2, 6, v1
	s_waitcnt vmcnt(0)
	v_lshl_add_u32 v18, s6, 3, v2
	s_mov_b32 s6, 0x10800
	v_cmp_gt_i32_e32 vcc, s6, v18
	s_and_saveexec_b64 s[6:7], vcc
	s_cbranch_execz .LBB0_605
	v_and_b32_e32 v2, 63, v1
	v_and_b32_e32 v1, 64, v214
	v_add_u32_e32 v3, 64, v1
	v_xor_b32_e32 v1, 32, v214
	v_cmp_lt_i32_e32 vcc, v1, v3
	v_xor_b32_e32 v4, 16, v214
	s_waitcnt lgkmcnt(0)
	s_load_dwordx4 s[8:11], s[0:1], 0xb8
	v_cndmask_b32_e32 v1, v214, v1, vcc
	v_cmp_lt_i32_e32 vcc, v4, v3
	v_mov_b32_e32 v5, v0
	v_or_b32_e32 v6, 64, v2
	v_cndmask_b32_e32 v4, v214, v4, vcc
	v_lshlrev_b32_e32 v40, 2, v4
	v_xor_b32_e32 v4, 8, v214
	v_cmp_lt_i32_e32 vcc, v4, v3
	v_or_b32_e32 v8, 0x80, v2
	v_or_b32_e32 v10, 0xc0, v2
	v_cndmask_b32_e32 v4, v214, v4, vcc
	v_lshlrev_b32_e32 v41, 2, v4
	v_xor_b32_e32 v4, 4, v214
	v_cmp_lt_i32_e32 vcc, v4, v3
	v_lshlrev_b32_e32 v1, 2, v1
	v_lshlrev_b32_e32 v24, 4, v2
	v_cndmask_b32_e32 v4, v214, v4, vcc
	v_lshlrev_b32_e32 v42, 2, v4
	v_xor_b32_e32 v4, 2, v214
	v_cmp_lt_i32_e32 vcc, v4, v3
	v_lshlrev_b32_e32 v26, 4, v6
	v_lshlrev_b32_e32 v28, 4, v8
	v_cndmask_b32_e32 v4, v214, v4, vcc
	v_lshlrev_b32_e32 v43, 2, v4
	v_xor_b32_e32 v4, 1, v214
	v_cmp_lt_i32_e32 vcc, v4, v3
	v_lshlrev_b32_e32 v30, 4, v10
	s_nop 0
	v_cndmask_b32_e32 v3, v214, v4, vcc
	v_lshlrev_b32_e32 v4, 4, v2
	v_lshlrev_b32_e32 v44, 2, v3
	s_waitcnt lgkmcnt(0)
	v_lshl_add_u64 v[20:21], s[8:9], 0, v[4:5]
	v_lshl_add_u64 v[22:23], s[10:11], 0, v[4:5]
	s_mov_b64 s[8:9], 0
	global_load_dwordx4 v[72:75], v[20:21], off
	global_load_dwordx4 v[76:79], v[20:21], off offset:1024
	global_load_dwordx4 v[80:83], v[20:21], off offset:2048
	global_load_dwordx4 v[84:87], v[20:21], off offset:3072
	v_ashrrev_i32_e32 v19, 31, v18
	v_lshlrev_b64 v[120:121], 12, v[18:19]
	v_lshl_add_u64 v[120:121], v[22:23], 0, v[120:121]
	global_load_dwordx4 v[88:91], v[120:121], off
	global_load_dwordx4 v[92:95], v[120:121], off offset:1024
	global_load_dwordx4 v[96:99], v[120:121], off offset:2048
	global_load_dwordx4 v[100:103], v[120:121], off offset:3072
	s_mov_b64 s[12:13], 0x800000
	s_movk_i32 s16, 16
	s_waitcnt vmcnt(0)
.Lp7_loop:
	v_lshl_add_u64 v[122:123], v[120:121], 0, s[12:13]
	global_load_dwordx4 v[104:107], v[122:123], off
	global_load_dwordx4 v[108:111], v[122:123], off offset:1024
	global_load_dwordx4 v[112:115], v[122:123], off offset:2048
	global_load_dwordx4 v[116:119], v[122:123], off offset:3072
	s_waitcnt vmcnt(8)
	v_mul_f32_e32 v124, v92, v92
	v_mul_f32_e32 v125, v88, v88
	v_mul_f32_e32 v126, v100, v100
	v_mul_f32_e32 v127, v96, v96
	v_fmac_f32_e32 v124, v93, v93
	v_fmac_f32_e32 v125, v89, v89
	v_fmac_f32_e32 v126, v101, v101
	v_fmac_f32_e32 v127, v97, v97
	v_fmac_f32_e32 v124, v94, v94
	v_fmac_f32_e32 v125, v90, v90
	v_fmac_f32_e32 v126, v102, v102
	v_fmac_f32_e32 v127, v98, v98
	v_fmac_f32_e32 v124, v95, v95
	v_fmac_f32_e32 v125, v91, v91
	v_fmac_f32_e32 v126, v103, v103
	v_fmac_f32_e32 v127, v99, v99
	v_add_f32_e32 v128, v124, v125
	v_add_f32_e32 v128, v127, v128
	v_add_f32_e32 v128, v126, v128
	ds_bpermute_b32 v129, v1, v128
	s_waitcnt lgkmcnt(0)
	v_add_f32_e32 v128, v128, v129
	ds_bpermute_b32 v129, v40, v128
	s_waitcnt lgkmcnt(0)
	v_add_f32_e32 v128, v128, v129
	ds_bpermute_b32 v129, v41, v128
	s_waitcnt lgkmcnt(0)
	v_add_f32_e32 v128, v128, v129
	ds_bpermute_b32 v129, v42, v128
	s_waitcnt lgkmcnt(0)
	v_add_f32_e32 v128, v128, v129
	ds_bpermute_b32 v129, v43, v128
	s_waitcnt lgkmcnt(0)
	v_add_f32_e32 v128, v128, v129
	ds_bpermute_b32 v129, v44, v128
	s_waitcnt lgkmcnt(0)
	v_add_f32_e32 v128, v128, v129
	v_fmamk_f32 v128, v128, 0x3a800000, v211
	v_cmp_gt_f32_e32 vcc, s26, v128
	v_mul_f32_e32 v129, 0x4b800000, v128
	s_nop 0
	v_cndmask_b32_e32 v128, v128, v129, vcc
	v_rsq_f32_e32 v128, v128
	s_nop 0
	v_mul_f32_e32 v129, 0x45800000, v128
	v_cndmask_b32_e32 v140, v128, v129, vcc
	s_nop 0
	v_pk_mul_f32 v[142:143], v[72:73], v[140:141] op_sel_hi:[1,0]
	v_pk_mul_f32 v[144:145], v[74:75], v[140:141] op_sel_hi:[1,0]
	v_pk_mul_f32 v[146:147], v[76:77], v[140:141] op_sel_hi:[1,0]
	v_pk_mul_f32 v[148:149], v[78:79], v[140:141] op_sel_hi:[1,0]
	v_pk_mul_f32 v[150:151], v[80:81], v[140:141] op_sel_hi:[1,0]
	v_pk_mul_f32 v[152:153], v[82:83], v[140:141] op_sel_hi:[1,0]
	v_pk_mul_f32 v[154:155], v[84:85], v[140:141] op_sel_hi:[1,0]
	v_pk_mul_f32 v[156:157], v[86:87], v[140:141] op_sel_hi:[1,0]
	v_pk_mul_f32 v[88:89], v[88:89], v[142:143]
	v_pk_mul_f32 v[90:91], v[90:91], v[144:145]
	v_pk_mul_f32 v[92:93], v[92:93], v[146:147]
	v_pk_mul_f32 v[94:95], v[94:95], v[148:149]
	v_pk_mul_f32 v[96:97], v[96:97], v[150:151]
	v_pk_mul_f32 v[98:99], v[98:99], v[152:153]
	v_pk_mul_f32 v[100:101], v[100:101], v[154:155]
	v_pk_mul_f32 v[102:103], v[102:103], v[156:157]
	global_store_dwordx4 v[120:121], v[88:91], off
	global_store_dwordx4 v[120:121], v[92:95], off offset:1024
	global_store_dwordx4 v[120:121], v[96:99], off offset:2048
	global_store_dwordx4 v[120:121], v[100:103], off offset:3072
	s_cmp_eq_u32 s16, 1
	s_cbranch_scc1 .Lp7_last
	v_lshl_add_u64 v[120:121], v[122:123], 0, s[12:13]
	global_load_dwordx4 v[88:91], v[120:121], off
	global_load_dwordx4 v[92:95], v[120:121], off offset:1024
	global_load_dwordx4 v[96:99], v[120:121], off offset:2048
	global_load_dwordx4 v[100:103], v[120:121], off offset:3072
	s_waitcnt vmcnt(8)
	s_branch .Lp7_procb
.Lp7_last:
	s_waitcnt vmcnt(4)
.Lp7_procb:
	v_mul_f32_e32 v124, v108, v108
	v_mul_f32_e32 v125, v104, v104
	v_mul_f32_e32 v126, v116, v116
	v_mul_f32_e32 v127, v112, v112
	v_fmac_f32_e32 v124, v109, v109
	v_fmac_f32_e32 v125, v105, v105
	v_fmac_f32_e32 v126, v117, v117
	v_fmac_f32_e32 v127, v113, v113
	v_fmac_f32_e32 v124, v110, v110
	v_fmac_f32_e32 v125, v106, v106
	v_fmac_f32_e32 v126, v118, v118
	v_fmac_f32_e32 v127, v114, v114
	v_fmac_f32_e32 v124, v111, v111
	v_fmac_f32_e32 v125, v107, v107
	v_fmac_f32_e32 v126, v119, v119
	v_fmac_f32_e32 v127, v115, v115
	v_add_f32_e32 v128, v124, v125
	v_add_f32_e32 v128, v127, v128
	v_add_f32_e32 v128, v126, v128
	ds_bpermute_b32 v129, v1, v128
	s_waitcnt lgkmcnt(0)
	v_add_f32_e32 v128, v128, v129
	ds_bpermute_b32 v129, v40, v128
	s_waitcnt lgkmcnt(0)
	v_add_f32_e32 v128, v128, v129
	ds_bpermute_b32 v129, v41, v128
	s_waitcnt lgkmcnt(0)
	v_add_f32_e32 v128, v128, v129
	ds_bpermute_b32 v129, v42, v128
	s_waitcnt lgkmcnt(0)
	v_add_f32_e32 v128, v128, v129
	ds_bpermute_b32 v129, v43, v128
	s_waitcnt lgkmcnt(0)
	v_add_f32_e32 v128, v128, v129
	ds_bpermute_b32 v129, v44, v128
	s_waitcnt lgkmcnt(0)
	v_add_f32_e32 v128, v128, v129
	v_fmamk_f32 v128, v128, 0x3a800000, v211
	v_cmp_gt_f32_e32 vcc, s26, v128
	v_mul_f32_e32 v129, 0x4b800000, v128
	s_nop 0
	v_cndmask_b32_e32 v128, v128, v129, vcc
	v_rsq_f32_e32 v128, v128
	s_nop 0
	v_mul_f32_e32 v129, 0x45800000, v128
	v_cndmask_b32_e32 v140, v128, v129, vcc
	s_nop 0
	v_pk_mul_f32 v[142:143], v[72:73], v[140:141] op_sel_hi:[1,0]
	v_pk_mul_f32 v[144:145], v[74:75], v[140:141] op_sel_hi:[1,0]
	v_pk_mul_f32 v[146:147], v[76:77], v[140:141] op_sel_hi:[1,0]
	v_pk_mul_f32 v[148:149], v[78:79], v[140:141] op_sel_hi:[1,0]
	v_pk_mul_f32 v[150:151], v[80:81], v[140:141] op_sel_hi:[1,0]
	v_pk_mul_f32 v[152:153], v[82:83], v[140:141] op_sel_hi:[1,0]
	v_pk_mul_f32 v[154:155], v[84:85], v[140:141] op_sel_hi:[1,0]
	v_pk_mul_f32 v[156:157], v[86:87], v[140:141] op_sel_hi:[1,0]
	v_pk_mul_f32 v[104:105], v[104:105], v[142:143]
	v_pk_mul_f32 v[106:107], v[106:107], v[144:145]
	v_pk_mul_f32 v[108:109], v[108:109], v[146:147]
	v_pk_mul_f32 v[110:111], v[110:111], v[148:149]
	v_pk_mul_f32 v[112:113], v[112:113], v[150:151]
	v_pk_mul_f32 v[114:115], v[114:115], v[152:153]
	v_pk_mul_f32 v[116:117], v[116:117], v[154:155]
	v_pk_mul_f32 v[118:119], v[118:119], v[156:157]
	global_store_dwordx4 v[122:123], v[104:107], off
	global_store_dwordx4 v[122:123], v[108:111], off offset:1024
	global_store_dwordx4 v[122:123], v[112:115], off offset:2048
	global_store_dwordx4 v[122:123], v[116:119], off offset:3072
	s_sub_u32 s16, s16, 1
	s_cmp_lg_u32 s16, 0
	s_cbranch_scc1 .Lp7_loop
	v_add_u32_e32 v18, 0x10000, v18
	s_branch .LBB0_603

.LBB0_610:
	s_or_b64 exec, exec, s[6:7]
	v_ashrrev_i32_e32 v3, 6, v4
	v_and_b32_e32 v2, 63, v4
	v_lshl_add_u32 v4, s52, 3, v3
	s_mov_b32 s6, 0x18800
	v_cmp_gt_i32_e32 vcc, s6, v4
	s_and_saveexec_b64 s[6:7], vcc
	s_cbranch_execz .LBB0_621
	s_load_dwordx2 s[16:17], s[0:1], 0x38
	s_waitcnt lgkmcnt(0)
	s_add_u32 s10, s8, 0x2b27800
	s_addc_u32 s11, s9, 0
	s_add_u32 s12, s8, 0x1b727800
	s_waitcnt vmcnt(0)
	v_lshlrev_b32_e32 v6, 4, v2
	v_mov_b32_e32 v7, v0
	s_addc_u32 s13, s9, 0
	v_lshl_add_u64 v[6:7], s[16:17], 0, v[6:7]
	s_mov_b64 s[16:17], 0
	v_readfirstlane_b32 s16, v4
	s_load_dwordx4 s[20:23], s[0:1], 0x0
	s_load_dwordx2 s[68:69], s[0:1], 0x10
	v_lshlrev_b32_e32 v72, 4, v2
	v_mov_b32_e32 v73, v0
	v_lshlrev_b32_e32 v74, 3, v2
	v_mov_b32_e32 v75, v0
	global_load_dwordx4 v[76:79], v[6:7], off
	global_load_dwordx4 v[80:83], v[6:7], off offset:1024
	global_load_dwordx4 v[84:87], v[6:7], off offset:2048
	global_load_dwordx4 v[88:91], v[6:7], off offset:3072
	v_xor_b32_e32 v160, 32, v214
	v_lshlrev_b32_e32 v160, 2, v160
	v_xor_b32_e32 v161, 16, v214
	v_lshlrev_b32_e32 v161, 2, v161
	v_xor_b32_e32 v162, 8, v214
	v_lshlrev_b32_e32 v162, 2, v162
	v_xor_b32_e32 v163, 4, v214
	v_lshlrev_b32_e32 v163, 2, v163
	v_xor_b32_e32 v164, 2, v214
	v_lshlrev_b32_e32 v164, 2, v164
	v_xor_b32_e32 v165, 1, v214
	v_lshlrev_b32_e32 v165, 2, v165
	s_waitcnt lgkmcnt(0)
	s_lshl_b32 s17, s16, 12
	s_add_u32 s20, s20, s17
	s_addc_u32 s21, s21, 0
	s_add_u32 s22, s22, s17
	s_addc_u32 s23, s23, 0
	s_add_u32 s68, s68, s17
	s_addc_u32 s69, s69, 0
	s_lshl_b32 s17, s16, 11
	s_add_u32 s10, s10, s17
	s_addc_u32 s11, s11, 0
	s_lshr_b32 s17, s16, 10
	s_mulk_i32 s17, 0x440
	s_and_b32 s16, s16, 0x3ff
	s_add_u32 s17, s17, s16
	s_add_u32 s17, s17, 0x10000
	s_lshl_b32 s17, s17, 11
	s_add_u32 s12, s12, s17
	s_addc_u32 s13, s13, 0
	v_lshl_add_u64 v[124:125], s[20:21], 0, v[72:73]
	v_lshl_add_u64 v[132:133], s[22:23], 0, v[72:73]
	v_lshl_add_u64 v[166:167], s[68:69], 0, v[72:73]
	v_lshl_add_u64 v[128:129], s[10:11], 0, v[74:75]
	v_lshl_add_u64 v[168:169], s[12:13], 0, v[74:75]
	global_load_dwordx4 v[92:95], v[124:125], off
	global_load_dwordx4 v[96:99], v[124:125], off offset:1024
	global_load_dwordx4 v[100:103], v[124:125], off offset:2048
	global_load_dwordx4 v[104:107], v[124:125], off offset:3072
	s_mov_b64 s[20:21], 0x800000
	s_mov_b64 s[22:23], 0x400000
	s_mov_b64 s[68:69], 0x440000
	s_movk_i32 s16, 16
	s_waitcnt vmcnt(0)
.Lp0_loop:
	v_lshl_add_u64 v[126:127], v[124:125], 0, s[20:21]
	v_lshl_add_u64 v[130:131], v[128:129], 0, s[22:23]
	global_load_dwordx4 v[108:111], v[126:127], off
	global_load_dwordx4 v[112:115], v[126:127], off offset:1024
	global_load_dwordx4 v[116:119], v[126:127], off offset:2048
	global_load_dwordx4 v[120:123], v[126:127], off offset:3072
	s_waitcnt vmcnt(8)
	v_mul_f32_e32 v172, v93, v93
	v_mul_f32_e32 v173, v97, v97
	v_mul_f32_e32 v174, v101, v101
	v_mul_f32_e32 v175, v105, v105
	v_fmac_f32_e32 v172, v92, v92
	v_fmac_f32_e32 v173, v96, v96
	v_fmac_f32_e32 v174, v100, v100
	v_fmac_f32_e32 v175, v104, v104
	v_fmac_f32_e32 v172, v94, v94
	v_fmac_f32_e32 v173, v98, v98
	v_fmac_f32_e32 v174, v102, v102
	v_fmac_f32_e32 v175, v106, v106
	v_fmac_f32_e32 v172, v95, v95
	v_fmac_f32_e32 v173, v99, v99
	v_fmac_f32_e32 v174, v103, v103
	v_fmac_f32_e32 v175, v107, v107
	v_add_f32_e32 v134, v172, v173
	v_add_f32_e32 v134, v134, v174
	v_add_f32_e32 v134, v134, v175
	ds_bpermute_b32 v135, v160, v134
	s_waitcnt lgkmcnt(0)
	v_add_f32_e32 v134, v134, v135
	ds_bpermute_b32 v135, v161, v134
	s_waitcnt lgkmcnt(0)
	v_add_f32_e32 v134, v134, v135
	ds_bpermute_b32 v135, v162, v134
	s_waitcnt lgkmcnt(0)
	v_add_f32_e32 v134, v134, v135
	ds_bpermute_b32 v135, v163, v134
	s_waitcnt lgkmcnt(0)
	v_add_f32_e32 v134, v134, v135
	ds_bpermute_b32 v135, v164, v134
	s_waitcnt lgkmcnt(0)
	v_add_f32_e32 v134, v134, v135
	ds_bpermute_b32 v135, v165, v134
	s_waitcnt lgkmcnt(0)
	v_add_f32_e32 v134, v134, v135
	v_fmamk_f32 v134, v134, 0x3a800000, v211
	v_mul_f32_e32 v135, 0x4b800000, v134
	v_cmp_gt_f32_e32 vcc, s26, v134
	s_nop 1
	v_cndmask_b32_e32 v134, v134, v135, vcc
	v_rsq_f32_e32 v134, v134
	s_nop 0
	v_mul_f32_e32 v135, 0x45800000, v134
	v_cndmask_b32_e32 v170, v134, v135, vcc
	v_mul_f32_e32 v136, v92, v170
	v_mul_f32_e32 v137, v93, v170
	v_mul_f32_e32 v138, v94, v170
	v_mul_f32_e32 v139, v95, v170
	v_mul_f32_e32 v140, v96, v170
	v_mul_f32_e32 v141, v97, v170
	v_mul_f32_e32 v142, v98, v170
	v_mul_f32_e32 v143, v99, v170
	v_mul_f32_e32 v144, v100, v170
	v_mul_f32_e32 v145, v101, v170
	v_mul_f32_e32 v146, v102, v170
	v_mul_f32_e32 v147, v103, v170
	v_mul_f32_e32 v148, v104, v170
	v_mul_f32_e32 v149, v105, v170
	v_mul_f32_e32 v150, v106, v170
	v_mul_f32_e32 v151, v107, v170
	v_mul_f32_e32 v136, v76, v136
	v_mul_f32_e32 v137, v77, v137
	v_mul_f32_e32 v138, v78, v138
	v_mul_f32_e32 v139, v79, v139
	v_mul_f32_e32 v140, v80, v140
	v_mul_f32_e32 v141, v81, v141
	v_mul_f32_e32 v142, v82, v142
	v_mul_f32_e32 v143, v83, v143
	v_mul_f32_e32 v144, v84, v144
	v_mul_f32_e32 v145, v85, v145
	v_mul_f32_e32 v146, v86, v146
	v_mul_f32_e32 v147, v87, v147
	v_mul_f32_e32 v148, v88, v148
	v_mul_f32_e32 v149, v89, v149
	v_mul_f32_e32 v150, v90, v150
	v_mul_f32_e32 v151, v91, v151
	v_cvt_pk_bf16_f32 v152, v136, v137
	v_cvt_pk_bf16_f32 v153, v138, v139
	v_cvt_pk_bf16_f32 v154, v140, v141
	v_cvt_pk_bf16_f32 v155, v142, v143
	v_cvt_pk_bf16_f32 v156, v144, v145
	v_cvt_pk_bf16_f32 v157, v146, v147
	v_cvt_pk_bf16_f32 v158, v148, v149
	v_cvt_pk_bf16_f32 v159, v150, v151
	global_store_dwordx2 v[128:129], v[152:153], off
	global_store_dwordx2 v[128:129], v[154:155], off offset:512
	global_store_dwordx2 v[128:129], v[156:157], off offset:1024
	global_store_dwordx2 v[128:129], v[158:159], off offset:1536
	s_cmp_eq_u32 s16, 1
	s_cbranch_scc1 .Lp0_lastsrc
	v_lshl_add_u64 v[124:125], v[126:127], 0, s[20:21]
	s_branch .Lp0_srcdone
.Lp0_lastsrc:
	v_mov_b32_e32 v124, v132
	v_mov_b32_e32 v125, v133
.Lp0_srcdone:
	v_lshl_add_u64 v[128:129], v[130:131], 0, s[22:23]
	global_load_dwordx4 v[92:95], v[124:125], off
	global_load_dwordx4 v[96:99], v[124:125], off offset:1024
	global_load_dwordx4 v[100:103], v[124:125], off offset:2048
	global_load_dwordx4 v[104:107], v[124:125], off offset:3072
	s_waitcnt vmcnt(8)
	v_mul_f32_e32 v172, v109, v109
	v_mul_f32_e32 v173, v113, v113
	v_mul_f32_e32 v174, v117, v117
	v_mul_f32_e32 v175, v121, v121
	v_fmac_f32_e32 v172, v108, v108
	v_fmac_f32_e32 v173, v112, v112
	v_fmac_f32_e32 v174, v116, v116
	v_fmac_f32_e32 v175, v120, v120
	v_fmac_f32_e32 v172, v110, v110
	v_fmac_f32_e32 v173, v114, v114
	v_fmac_f32_e32 v174, v118, v118
	v_fmac_f32_e32 v175, v122, v122
	v_fmac_f32_e32 v172, v111, v111
	v_fmac_f32_e32 v173, v115, v115
	v_fmac_f32_e32 v174, v119, v119
	v_fmac_f32_e32 v175, v123, v123
	v_add_f32_e32 v134, v172, v173
	v_add_f32_e32 v134, v134, v174
	v_add_f32_e32 v134, v134, v175
	ds_bpermute_b32 v135, v160, v134
	s_waitcnt lgkmcnt(0)
	v_add_f32_e32 v134, v134, v135
	ds_bpermute_b32 v135, v161, v134
	s_waitcnt lgkmcnt(0)
	v_add_f32_e32 v134, v134, v135
	ds_bpermute_b32 v135, v162, v134
	s_waitcnt lgkmcnt(0)
	v_add_f32_e32 v134, v134, v135
	ds_bpermute_b32 v135, v163, v134
	s_waitcnt lgkmcnt(0)
	v_add_f32_e32 v134, v134, v135
	ds_bpermute_b32 v135, v164, v134
	s_waitcnt lgkmcnt(0)
	v_add_f32_e32 v134, v134, v135
	ds_bpermute_b32 v135, v165, v134
	s_waitcnt lgkmcnt(0)
	v_add_f32_e32 v134, v134, v135
	v_fmamk_f32 v134, v134, 0x3a800000, v211
	v_mul_f32_e32 v135, 0x4b800000, v134
	v_cmp_gt_f32_e32 vcc, s26, v134
	s_nop 1
	v_cndmask_b32_e32 v134, v134, v135, vcc
	v_rsq_f32_e32 v134, v134
	s_nop 0
	v_mul_f32_e32 v135, 0x45800000, v134
	v_cndmask_b32_e32 v170, v134, v135, vcc
	v_mul_f32_e32 v136, v108, v170
	v_mul_f32_e32 v137, v109, v170
	v_mul_f32_e32 v138, v110, v170
	v_mul_f32_e32 v139, v111, v170
	v_mul_f32_e32 v140, v112, v170
	v_mul_f32_e32 v141, v113, v170
	v_mul_f32_e32 v142, v114, v170
	v_mul_f32_e32 v143, v115, v170
	v_mul_f32_e32 v144, v116, v170
	v_mul_f32_e32 v145, v117, v170
	v_mul_f32_e32 v146, v118, v170
	v_mul_f32_e32 v147, v119, v170
	v_mul_f32_e32 v148, v120, v170
	v_mul_f32_e32 v149, v121, v170
	v_mul_f32_e32 v150, v122, v170
	v_mul_f32_e32 v151, v123, v170
	v_mul_f32_e32 v136, v76, v136
	v_mul_f32_e32 v137, v77, v137
	v_mul_f32_e32 v138, v78, v138
	v_mul_f32_e32 v139, v79, v139
	v_mul_f32_e32 v140, v80, v140
	v_mul_f32_e32 v141, v81, v141
	v_mul_f32_e32 v142, v82, v142
	v_mul_f32_e32 v143, v83, v143
	v_mul_f32_e32 v144, v84, v144
	v_mul_f32_e32 v145, v85, v145
	v_mul_f32_e32 v146, v86, v146
	v_mul_f32_e32 v147, v87, v147
	v_mul_f32_e32 v148, v88, v148
	v_mul_f32_e32 v149, v89, v149
	v_mul_f32_e32 v150, v90, v150
	v_mul_f32_e32 v151, v91, v151
	v_cvt_pk_bf16_f32 v152, v136, v137
	v_cvt_pk_bf16_f32 v153, v138, v139
	v_cvt_pk_bf16_f32 v154, v140, v141
	v_cvt_pk_bf16_f32 v155, v142, v143
	v_cvt_pk_bf16_f32 v156, v144, v145
	v_cvt_pk_bf16_f32 v157, v146, v147
	v_cvt_pk_bf16_f32 v158, v148, v149
	v_cvt_pk_bf16_f32 v159, v150, v151
	global_store_dwordx2 v[130:131], v[152:153], off
	global_store_dwordx2 v[130:131], v[154:155], off offset:512
	global_store_dwordx2 v[130:131], v[156:157], off offset:1024
	global_store_dwordx2 v[130:131], v[158:159], off offset:1536
	s_sub_u32 s16, s16, 1
	s_cmp_lg_u32 s16, 0
	s_cbranch_scc1 .Lp0_loop
	global_load_dwordx4 v[108:111], v[166:167], off
	global_load_dwordx4 v[112:115], v[166:167], off offset:1024
	global_load_dwordx4 v[116:119], v[166:167], off offset:2048
	global_load_dwordx4 v[120:123], v[166:167], off offset:3072
	s_waitcnt vmcnt(8)
	v_mul_f32_e32 v172, v93, v93
	v_mul_f32_e32 v173, v97, v97
	v_mul_f32_e32 v174, v101, v101
	v_mul_f32_e32 v175, v105, v105
	v_fmac_f32_e32 v172, v92, v92
	v_fmac_f32_e32 v173, v96, v96
	v_fmac_f32_e32 v174, v100, v100
	v_fmac_f32_e32 v175, v104, v104
	v_fmac_f32_e32 v172, v94, v94
	v_fmac_f32_e32 v173, v98, v98
	v_fmac_f32_e32 v174, v102, v102
	v_fmac_f32_e32 v175, v106, v106
	v_fmac_f32_e32 v172, v95, v95
	v_fmac_f32_e32 v173, v99, v99
	v_fmac_f32_e32 v174, v103, v103
	v_fmac_f32_e32 v175, v107, v107
	v_add_f32_e32 v134, v172, v173
	v_add_f32_e32 v134, v134, v174
	v_add_f32_e32 v134, v134, v175
	ds_bpermute_b32 v135, v160, v134
	s_waitcnt lgkmcnt(0)
	v_add_f32_e32 v134, v134, v135
	ds_bpermute_b32 v135, v161, v134
	s_waitcnt lgkmcnt(0)
	v_add_f32_e32 v134, v134, v135
	ds_bpermute_b32 v135, v162, v134
	s_waitcnt lgkmcnt(0)
	v_add_f32_e32 v134, v134, v135
	ds_bpermute_b32 v135, v163, v134
	s_waitcnt lgkmcnt(0)
	v_add_f32_e32 v134, v134, v135
	ds_bpermute_b32 v135, v164, v134
	s_waitcnt lgkmcnt(0)
	v_add_f32_e32 v134, v134, v135
	ds_bpermute_b32 v135, v165, v134
	s_waitcnt lgkmcnt(0)
	v_add_f32_e32 v134, v134, v135
	v_fmamk_f32 v134, v134, 0x3a800000, v211
	v_mul_f32_e32 v135, 0x4b800000, v134
	v_cmp_gt_f32_e32 vcc, s26, v134
	s_nop 1
	v_cndmask_b32_e32 v134, v134, v135, vcc
	v_rsq_f32_e32 v134, v134
	s_nop 0
	v_mul_f32_e32 v135, 0x45800000, v134
	v_cndmask_b32_e32 v170, v134, v135, vcc
	v_mul_f32_e32 v136, v92, v170
	v_mul_f32_e32 v137, v93, v170
	v_mul_f32_e32 v138, v94, v170
	v_mul_f32_e32 v139, v95, v170
	v_mul_f32_e32 v140, v96, v170
	v_mul_f32_e32 v141, v97, v170
	v_mul_f32_e32 v142, v98, v170
	v_mul_f32_e32 v143, v99, v170
	v_mul_f32_e32 v144, v100, v170
	v_mul_f32_e32 v145, v101, v170
	v_mul_f32_e32 v146, v102, v170
	v_mul_f32_e32 v147, v103, v170
	v_mul_f32_e32 v148, v104, v170
	v_mul_f32_e32 v149, v105, v170
	v_mul_f32_e32 v150, v106, v170
	v_mul_f32_e32 v151, v107, v170
	v_mul_f32_e32 v136, v76, v136
	v_mul_f32_e32 v137, v77, v137
	v_mul_f32_e32 v138, v78, v138
	v_mul_f32_e32 v139, v79, v139
	v_mul_f32_e32 v140, v80, v140
	v_mul_f32_e32 v141, v81, v141
	v_mul_f32_e32 v142, v82, v142
	v_mul_f32_e32 v143, v83, v143
	v_mul_f32_e32 v144, v84, v144
	v_mul_f32_e32 v145, v85, v145
	v_mul_f32_e32 v146, v86, v146
	v_mul_f32_e32 v147, v87, v147
	v_mul_f32_e32 v148, v88, v148
	v_mul_f32_e32 v149, v89, v149
	v_mul_f32_e32 v150, v90, v150
	v_mul_f32_e32 v151, v91, v151
	v_cvt_pk_bf16_f32 v152, v136, v137
	v_cvt_pk_bf16_f32 v153, v138, v139
	v_cvt_pk_bf16_f32 v154, v140, v141
	v_cvt_pk_bf16_f32 v155, v142, v143
	v_cvt_pk_bf16_f32 v156, v144, v145
	v_cvt_pk_bf16_f32 v157, v146, v147
	v_cvt_pk_bf16_f32 v158, v148, v149
	v_cvt_pk_bf16_f32 v159, v150, v151
	global_store_dwordx2 v[128:129], v[152:153], off
	global_store_dwordx2 v[128:129], v[154:155], off offset:512
	global_store_dwordx2 v[128:129], v[156:157], off offset:1024
	global_store_dwordx2 v[128:129], v[158:159], off offset:1536
	s_movk_i32 s16, 8
.Lp0_cloop:
	v_lshl_add_u64 v[166:167], v[166:167], 0, s[20:21]
	global_load_dwordx4 v[92:95], v[166:167], off
	global_load_dwordx4 v[96:99], v[166:167], off offset:1024
	global_load_dwordx4 v[100:103], v[166:167], off offset:2048
	global_load_dwordx4 v[104:107], v[166:167], off offset:3072
	s_waitcnt vmcnt(8)
	v_cvt_pk_bf16_f32 v152, v108, v109
	v_cvt_pk_bf16_f32 v153, v110, v111
	v_cvt_pk_bf16_f32 v154, v112, v113
	v_cvt_pk_bf16_f32 v155, v114, v115
	v_cvt_pk_bf16_f32 v156, v116, v117
	v_cvt_pk_bf16_f32 v157, v118, v119
	v_cvt_pk_bf16_f32 v158, v120, v121
	v_cvt_pk_bf16_f32 v159, v122, v123
	global_store_dwordx2 v[168:169], v[152:153], off
	global_store_dwordx2 v[168:169], v[154:155], off offset:512
	global_store_dwordx2 v[168:169], v[156:157], off offset:1024
	global_store_dwordx2 v[168:169], v[158:159], off offset:1536
	v_lshl_add_u64 v[168:169], v[168:169], 0, s[68:69]
	s_cmp_eq_u32 s16, 1
	s_cbranch_scc1 .Lp0_clast
	v_lshl_add_u64 v[166:167], v[166:167], 0, s[20:21]
	global_load_dwordx4 v[108:111], v[166:167], off
	global_load_dwordx4 v[112:115], v[166:167], off offset:1024
	global_load_dwordx4 v[116:119], v[166:167], off offset:2048
	global_load_dwordx4 v[120:123], v[166:167], off offset:3072
	s_waitcnt vmcnt(8)
	s_branch .Lp0_cproc

.Lp0_cproc:
	v_cvt_pk_bf16_f32 v152, v92, v93
	v_cvt_pk_bf16_f32 v153, v94, v95
	v_cvt_pk_bf16_f32 v154, v96, v97
	v_cvt_pk_bf16_f32 v155, v98, v99
	v_cvt_pk_bf16_f32 v156, v100, v101
	v_cvt_pk_bf16_f32 v157, v102, v103
	v_cvt_pk_bf16_f32 v158, v104, v105
	v_cvt_pk_bf16_f32 v159, v106, v107
	global_store_dwordx2 v[168:169], v[152:153], off
	global_store_dwordx2 v[168:169], v[154:155], off offset:512
	global_store_dwordx2 v[168:169], v[156:157], off offset:1024
	global_store_dwordx2 v[168:169], v[158:159], off offset:1536
	v_lshl_add_u64 v[168:169], v[168:169], 0, s[68:69]
	s_sub_u32 s16, s16, 1
	s_cmp_lg_u32 s16, 0
	s_cbranch_scc1 .Lp0_cloop
	s_branch .LBB0_621
